# k0: nt hint on the read-once f32 input loads (weights, x)
# speedup vs baseline: 1.0467x; 1.0087x over previous
.LBB0_3:
	s_add_i32 s94, s6, 0x2000
	s_cmpk_gt_i32 s94, 0x5ff
	s_mov_b64 s[4:5], -1
	s_cbranch_scc0 .LBB0_21
	s_cmpk_gt_u32 s94, 0xbff
	s_cbranch_scc0 .LBB0_18
	s_cmpk_gt_u32 s94, 0xdff
	s_cbranch_scc0 .LBB0_15
	s_cmpk_gt_u32 s94, 0xfff
	s_cbranch_scc0 .LBB0_12
	s_cmpk_gt_u32 s94, 0x1fff
	s_cbranch_scc0 .LBB0_9
	s_load_dwordx2 s[4:5], s[0:1], 0xc8
	s_lshr_b32 s2, s6, 11
	s_lshl_b64 s[96:97], s[2:3], 24
	v_mov_b32_e32 v35, v3
	s_waitcnt lgkmcnt(0)
	s_add_u32 s96, s4, s96
	s_addc_u32 s97, s5, s97
	s_cmpk_lt_u32 s6, 0x800
	s_cselect_b32 s2, s15, 0x2900000
	s_add_u32 s4, s24, s2
	s_addc_u32 s5, s25, 0
	s_add_i32 s2, s9, s93
	s_and_b32 s2, s2, 0x3e0
	s_and_b32 s95, s7, 0xfc0
	s_lshl_b32 s98, s2, 2
	s_add_u32 s96, s96, s98
	v_or_b32_e32 v13, s95, v1
	s_addc_u32 s97, s97, 0
	v_lshl_add_u64 v[32:33], s[96:97], 0, v[2:3]
	v_lshlrev_b32_e32 v34, 12, v13
	v_lshl_add_u64 v[32:33], v[32:33], 0, v[34:35]
	v_add_co_u32_e32 v34, vcc, s14, v32
	s_lshl_b32 s95, s95, 1
	s_nop 0
	v_addc_co_u32_e32 v35, vcc, 0, v33, vcc
	v_add_co_u32_e32 v36, vcc, s16, v32
	s_add_u32 s4, s4, s95
	s_nop 0
	v_addc_co_u32_e32 v37, vcc, 0, v33, vcc
	v_add_co_u32_e32 v38, vcc, s17, v32
	s_addc_u32 s5, s5, 0
	s_nop 0
	v_addc_co_u32_e32 v39, vcc, 0, v33, vcc
	v_add_co_u32_e32 v40, vcc, s18, v32
	s_nop 1
	v_addc_co_u32_e32 v41, vcc, 0, v33, vcc
	v_add_co_u32_e32 v42, vcc, s19, v32
	s_nop 1
	v_addc_co_u32_e32 v43, vcc, 0, v33, vcc
	v_add_co_u32_e32 v44, vcc, s21, v32
	s_nop 1
	v_addc_co_u32_e32 v45, vcc, 0, v33, vcc
	v_add_co_u32_e32 v46, vcc, s23, v32
	s_nop 1
	v_addc_co_u32_e32 v47, vcc, 0, v33, vcc
	global_load_dword v13, v[32:33], off nt
	global_load_dword v31, v[34:35], off nt
	global_load_dword v50, v[36:37], off nt
	global_load_dword v51, v[38:39], off nt
	global_load_dword v52, v[40:41], off nt
	global_load_dword v53, v[42:43], off nt
	global_load_dword v54, v[44:45], off nt
	global_load_dword v55, v[46:47], off nt
	v_add_co_u32_e32 v34, vcc, s26, v32
	s_nop 1
	v_addc_co_u32_e32 v35, vcc, 0, v33, vcc
	v_add_co_u32_e32 v36, vcc, s27, v32
	s_nop 1
	v_addc_co_u32_e32 v37, vcc, 0, v33, vcc
	v_add_co_u32_e32 v38, vcc, s28, v32
	s_nop 1
	v_addc_co_u32_e32 v39, vcc, 0, v33, vcc
	v_add_co_u32_e32 v40, vcc, s29, v32
	s_nop 1
	v_addc_co_u32_e32 v41, vcc, 0, v33, vcc
	v_add_co_u32_e32 v42, vcc, s30, v32
	s_nop 1
	v_addc_co_u32_e32 v43, vcc, 0, v33, vcc
	v_add_co_u32_e32 v44, vcc, s31, v32
	s_nop 1
	v_addc_co_u32_e32 v45, vcc, 0, v33, vcc
	v_add_co_u32_e32 v46, vcc, s33, v32
	s_nop 1
	v_addc_co_u32_e32 v47, vcc, 0, v33, vcc
	v_add_co_u32_e32 v48, vcc, s34, v32
	s_nop 1
	v_addc_co_u32_e32 v49, vcc, 0, v33, vcc
	global_load_dword v57, v[34:35], off nt
	global_load_dword v58, v[36:37], off nt
	global_load_dword v59, v[38:39], off nt
	global_load_dword v60, v[40:41], off nt
	global_load_dword v61, v[42:43], off nt
	global_load_dword v62, v[44:45], off nt
	global_load_dword v63, v[46:47], off nt
	global_load_dword v64, v[48:49], off nt
	v_add_co_u32_e32 v34, vcc, s35, v32
	s_nop 1
	v_addc_co_u32_e32 v35, vcc, 0, v33, vcc
	v_add_co_u32_e32 v36, vcc, s36, v32
	s_nop 1
	v_addc_co_u32_e32 v37, vcc, 0, v33, vcc
	v_add_co_u32_e32 v38, vcc, s37, v32
	s_nop 1
	v_addc_co_u32_e32 v39, vcc, 0, v33, vcc
	v_add_co_u32_e32 v40, vcc, s38, v32
	s_nop 1
	v_addc_co_u32_e32 v41, vcc, 0, v33, vcc
	v_add_co_u32_e32 v42, vcc, s39, v32
	s_nop 1
	v_addc_co_u32_e32 v43, vcc, 0, v33, vcc
	v_add_co_u32_e32 v44, vcc, s40, v32
	s_nop 1
	v_addc_co_u32_e32 v45, vcc, 0, v33, vcc
	v_add_co_u32_e32 v46, vcc, s41, v32
	s_nop 1
	v_addc_co_u32_e32 v47, vcc, 0, v33, vcc
	v_add_co_u32_e32 v48, vcc, s42, v32
	s_nop 1
	v_addc_co_u32_e32 v49, vcc, 0, v33, vcc
	global_load_dword v65, v[34:35], off nt
	global_load_dword v66, v[36:37], off nt
	global_load_dword v67, v[38:39], off nt
	global_load_dword v68, v[40:41], off nt
	global_load_dword v69, v[42:43], off nt
	global_load_dword v70, v[44:45], off nt
	global_load_dword v71, v[46:47], off nt
	s_nop 0
	global_load_dword v48, v[48:49], off nt
	v_add_co_u32_e32 v34, vcc, s43, v32
	s_nop 1
	v_addc_co_u32_e32 v35, vcc, 0, v33, vcc
	v_add_co_u32_e32 v36, vcc, s44, v32
	s_nop 1
	v_addc_co_u32_e32 v37, vcc, 0, v33, vcc
	v_add_co_u32_e32 v38, vcc, s45, v32
	s_nop 1
	v_addc_co_u32_e32 v39, vcc, 0, v33, vcc
	v_add_co_u32_e32 v40, vcc, s46, v32
	s_nop 1
	v_addc_co_u32_e32 v41, vcc, 0, v33, vcc
	v_add_co_u32_e32 v42, vcc, s47, v32
	s_nop 1
	v_addc_co_u32_e32 v43, vcc, 0, v33, vcc
	v_add_co_u32_e32 v44, vcc, s48, v32
	s_nop 1
	v_addc_co_u32_e32 v45, vcc, 0, v33, vcc
	v_add_co_u32_e32 v46, vcc, s49, v32
	s_nop 1
	v_addc_co_u32_e32 v47, vcc, 0, v33, vcc
	v_add_co_u32_e32 v32, vcc, s50, v32
	s_nop 1
	v_addc_co_u32_e32 v33, vcc, 0, v33, vcc
	global_load_dword v34, v[34:35], off nt
	s_nop 0
	global_load_dword v35, v[36:37], off nt
	s_nop 0
	global_load_dword v36, v[38:39], off nt
	global_load_dword v37, v[40:41], off nt
	s_nop 0
	global_load_dword v38, v[42:43], off nt
	global_load_dword v39, v[44:45], off nt
	global_load_dword v40, v[46:47], off nt
	s_nop 0
	global_load_dword v32, v[32:33], off nt
	s_waitcnt vmcnt(30)
	ds_write2_b32 v14, v13, v31 offset1:66
	s_waitcnt vmcnt(28)
	ds_write2_b32 v14, v50, v51 offset0:132 offset1:198
	s_waitcnt vmcnt(26)
	ds_write2_b32 v24, v52, v53 offset0:8 offset1:74
	s_waitcnt vmcnt(24)
	ds_write2_b32 v24, v54, v55 offset0:140 offset1:206
	s_waitcnt vmcnt(22)
	ds_write2_b32 v25, v57, v58 offset0:16 offset1:82
	s_waitcnt vmcnt(20)
	ds_write2_b32 v25, v59, v60 offset0:148 offset1:214
	s_waitcnt vmcnt(18)
	ds_write2_b32 v26, v61, v62 offset0:24 offset1:90
	s_waitcnt vmcnt(16)
	ds_write2_b32 v26, v63, v64 offset0:156 offset1:222
	s_waitcnt vmcnt(14)
	ds_write2_b32 v27, v65, v66 offset0:32 offset1:98
	s_waitcnt vmcnt(12)
	ds_write2_b32 v27, v67, v68 offset0:164 offset1:230
	s_waitcnt vmcnt(10)
	ds_write2_b32 v28, v69, v70 offset0:40 offset1:106
	s_waitcnt vmcnt(8)
	ds_write2_b32 v28, v71, v48 offset0:172 offset1:238
	s_waitcnt vmcnt(6)
	ds_write2_b32 v29, v34, v35 offset0:48 offset1:114
	s_waitcnt vmcnt(4)
	ds_write2_b32 v29, v36, v37 offset0:180 offset1:246
	s_waitcnt vmcnt(2)
	ds_write2_b32 v30, v38, v39 offset0:56 offset1:122
	s_waitcnt vmcnt(0)
	ds_write2_b32 v30, v40, v32 offset0:188 offset1:254
	s_waitcnt lgkmcnt(0)
	ds_read2_b32 v[36:37], v16 offset0:33 offset1:41
	ds_read2_b32 v[38:39], v16 offset1:8
	ds_read2_b32 v[40:41], v16 offset0:66 offset1:74
	ds_read2_b32 v[42:43], v16 offset0:99 offset1:107
	ds_read2_b32 v[44:45], v16 offset0:132 offset1:140
	ds_read2_b32 v[46:47], v16 offset0:165 offset1:173
	ds_read2_b32 v[48:49], v16 offset0:198 offset1:206
	ds_read2_b32 v[50:51], v16 offset0:231 offset1:239
	v_mov_b32_e32 v13, v3
	v_lshl_add_u64 v[52:53], s[4:5], 0, v[12:13]
	v_or_b32_e32 v13, s2, v15
	v_lshlrev_b32_e32 v54, 13, v13
	v_mov_b32_e32 v55, v3
	s_waitcnt lgkmcnt(6)
	v_cvt_pk_bf16_f32 v32, v38, v36
	s_waitcnt lgkmcnt(4)
	v_cvt_pk_bf16_f32 v33, v40, v42
	s_waitcnt lgkmcnt(2)
	v_cvt_pk_bf16_f32 v34, v44, v46
	s_waitcnt lgkmcnt(0)
	v_cvt_pk_bf16_f32 v35, v48, v50
	v_lshl_add_u64 v[54:55], v[52:53], 0, v[54:55]
	global_store_dwordx4 v[54:55], v[32:35], off
	v_or_b32_e32 v13, s2, v17
	v_lshlrev_b32_e32 v36, 13, v13
	v_cvt_pk_bf16_f32 v32, v39, v37
	v_cvt_pk_bf16_f32 v33, v41, v43
	v_cvt_pk_bf16_f32 v34, v45, v47
	v_cvt_pk_bf16_f32 v35, v49, v51
	ds_read2_b32 v[38:39], v16 offset0:49 offset1:57
	ds_read2_b32 v[40:41], v16 offset0:16 offset1:24
	ds_read2_b32 v[42:43], v16 offset0:82 offset1:90
	ds_read2_b32 v[44:45], v16 offset0:115 offset1:123
	ds_read2_b32 v[46:47], v16 offset0:148 offset1:156
	ds_read2_b32 v[48:49], v16 offset0:181 offset1:189
	ds_read2_b32 v[50:51], v16 offset0:214 offset1:222
	ds_read2_b32 v[54:55], v16 offset0:247 offset1:255
	v_mov_b32_e32 v37, v3
	v_lshl_add_u64 v[36:37], v[52:53], 0, v[36:37]
	v_or_b32_e32 v13, s2, v18
	global_store_dwordx4 v[36:37], v[32:35], off
	v_lshlrev_b32_e32 v36, 13, v13
	v_mov_b32_e32 v37, v3
	s_waitcnt lgkmcnt(6)
	v_cvt_pk_bf16_f32 v32, v40, v38
	s_waitcnt lgkmcnt(4)
	v_cvt_pk_bf16_f32 v33, v42, v44
	s_waitcnt lgkmcnt(2)
	v_cvt_pk_bf16_f32 v34, v46, v48
	s_waitcnt lgkmcnt(0)
	v_cvt_pk_bf16_f32 v35, v50, v54
	v_lshl_add_u64 v[36:37], v[52:53], 0, v[36:37]
	v_or_b32_e32 v13, s2, v19
	global_store_dwordx4 v[36:37], v[32:35], off
	v_lshlrev_b32_e32 v36, 13, v13
	v_mov_b32_e32 v37, v3
	v_cvt_pk_bf16_f32 v32, v41, v39
	v_cvt_pk_bf16_f32 v33, v43, v45
	v_cvt_pk_bf16_f32 v34, v47, v49
	v_cvt_pk_bf16_f32 v35, v51, v55
	v_lshl_add_u64 v[36:37], v[52:53], 0, v[36:37]
	global_store_dwordx4 v[36:37], v[32:35], off
	s_waitcnt lgkmcnt(0)
	s_mov_b64 s[4:5], 0
.LBB0_9:
	s_andn2_b64 vcc, exec, s[4:5]
	s_cbranch_vccnz .LBB0_11
	s_load_dwordx2 s[4:5], s[0:1], 0xc0
	s_add_i32 s95, s6, 0x1000
	s_lshr_b32 s2, s95, 1
	s_and_b32 s2, s2, 0x7ffffc00
	s_lshl_b64 s[96:97], s[2:3], 14
	s_waitcnt lgkmcnt(0)
	s_add_u32 s96, s4, s96
	s_addc_u32 s97, s5, s97
	s_cmpk_lt_u32 s95, 0x800
	s_cselect_b32 s2, s51, 0x2100000
	s_add_u32 s4, s24, s2
	s_addc_u32 s5, s25, 0
	s_lshr_b32 s2, s94, 1
	s_and_b32 s95, s2, 0x3c0
	s_add_i32 s2, s9, s93
	s_and_b32 s2, s2, 0xfe0
	s_lshl_b32 s98, s2, 2
	s_add_u32 s96, s96, s98
	v_or_b32_e32 v13, s95, v1
	s_addc_u32 s97, s97, 0
	v_lshl_add_u64 v[32:33], s[96:97], 0, v[2:3]
	v_lshlrev_b32_e32 v34, 14, v13
	v_mov_b32_e32 v35, v3
	v_lshl_add_u64 v[32:33], v[32:33], 0, v[34:35]
	v_add_co_u32_e32 v34, vcc, s18, v32
	s_lshl_b32 s95, s95, 1
	s_nop 0
	v_addc_co_u32_e32 v35, vcc, 0, v33, vcc
	v_add_co_u32_e32 v36, vcc, s26, v32
	s_add_u32 s4, s4, s95
	s_nop 0
	v_addc_co_u32_e32 v37, vcc, 0, v33, vcc
	v_add_co_u32_e32 v38, vcc, s30, v32
	s_addc_u32 s5, s5, 0
	s_nop 0
	v_addc_co_u32_e32 v39, vcc, 0, v33, vcc
	v_add_co_u32_e32 v40, vcc, s35, v32
	s_nop 1
	v_addc_co_u32_e32 v41, vcc, 0, v33, vcc
	v_add_co_u32_e32 v42, vcc, s39, v32
	s_nop 1
	v_addc_co_u32_e32 v43, vcc, 0, v33, vcc
	v_add_co_u32_e32 v44, vcc, s43, v32
	s_nop 1
	v_addc_co_u32_e32 v45, vcc, 0, v33, vcc
	v_add_co_u32_e32 v46, vcc, s47, v32
	s_nop 1
	v_addc_co_u32_e32 v47, vcc, 0, v33, vcc
	global_load_dword v13, v[32:33], off nt
	global_load_dword v31, v[34:35], off nt
	global_load_dword v50, v[36:37], off nt
	global_load_dword v51, v[38:39], off nt
	global_load_dword v52, v[40:41], off nt
	global_load_dword v53, v[42:43], off nt
	global_load_dword v54, v[44:45], off nt
	global_load_dword v55, v[46:47], off nt
	v_add_co_u32_e32 v34, vcc, s52, v32
	s_nop 1
	v_addc_co_u32_e32 v35, vcc, 0, v33, vcc
	v_add_co_u32_e32 v36, vcc, s53, v32
	s_nop 1
	v_addc_co_u32_e32 v37, vcc, 0, v33, vcc
	v_add_co_u32_e32 v38, vcc, s54, v32
	s_nop 1
	v_addc_co_u32_e32 v39, vcc, 0, v33, vcc
	v_add_co_u32_e32 v40, vcc, s55, v32
	s_nop 1
	v_addc_co_u32_e32 v41, vcc, 0, v33, vcc
	v_add_co_u32_e32 v42, vcc, s56, v32
	s_nop 1
	v_addc_co_u32_e32 v43, vcc, 0, v33, vcc
	v_add_co_u32_e32 v44, vcc, s57, v32
	s_nop 1
	v_addc_co_u32_e32 v45, vcc, 0, v33, vcc
	v_add_co_u32_e32 v46, vcc, s58, v32
	s_nop 1
	v_addc_co_u32_e32 v47, vcc, 0, v33, vcc
	v_add_co_u32_e32 v48, vcc, s59, v32
	s_nop 1
	v_addc_co_u32_e32 v49, vcc, 0, v33, vcc
	global_load_dword v57, v[34:35], off nt
	global_load_dword v58, v[36:37], off nt
	global_load_dword v59, v[38:39], off nt
	global_load_dword v60, v[40:41], off nt
	global_load_dword v61, v[42:43], off nt
	global_load_dword v62, v[44:45], off nt
	global_load_dword v63, v[46:47], off nt
	global_load_dword v64, v[48:49], off nt
	v_add_co_u32_e32 v34, vcc, s60, v32
	s_nop 1
	v_addc_co_u32_e32 v35, vcc, 0, v33, vcc
	v_add_co_u32_e32 v36, vcc, s61, v32
	s_nop 1
	v_addc_co_u32_e32 v37, vcc, 0, v33, vcc
	v_add_co_u32_e32 v38, vcc, s62, v32
	s_nop 1
	v_addc_co_u32_e32 v39, vcc, 0, v33, vcc
	v_add_co_u32_e32 v40, vcc, s63, v32
	s_nop 1
	v_addc_co_u32_e32 v41, vcc, 0, v33, vcc
	v_add_co_u32_e32 v42, vcc, s64, v32
	s_nop 1
	v_addc_co_u32_e32 v43, vcc, 0, v33, vcc
	v_add_co_u32_e32 v44, vcc, s65, v32
	s_nop 1
	v_addc_co_u32_e32 v45, vcc, 0, v33, vcc
	v_add_co_u32_e32 v46, vcc, s66, v32
	s_nop 1
	v_addc_co_u32_e32 v47, vcc, 0, v33, vcc
	v_add_co_u32_e32 v48, vcc, s67, v32
	s_nop 1
	v_addc_co_u32_e32 v49, vcc, 0, v33, vcc
	global_load_dword v65, v[34:35], off nt
	global_load_dword v66, v[36:37], off nt
	global_load_dword v67, v[38:39], off nt
	global_load_dword v68, v[40:41], off nt
	global_load_dword v69, v[42:43], off nt
	global_load_dword v70, v[44:45], off nt
	global_load_dword v71, v[46:47], off nt
	s_nop 0
	global_load_dword v48, v[48:49], off nt
	v_add_co_u32_e32 v34, vcc, s68, v32
	s_nop 1
	v_addc_co_u32_e32 v35, vcc, 0, v33, vcc
	v_add_co_u32_e32 v36, vcc, s69, v32
	s_nop 1
	v_addc_co_u32_e32 v37, vcc, 0, v33, vcc
	v_add_co_u32_e32 v38, vcc, s70, v32
	s_nop 1
	v_addc_co_u32_e32 v39, vcc, 0, v33, vcc
	v_add_co_u32_e32 v40, vcc, s71, v32
	s_nop 1
	v_addc_co_u32_e32 v41, vcc, 0, v33, vcc
	v_add_co_u32_e32 v42, vcc, s72, v32
	s_nop 1
	v_addc_co_u32_e32 v43, vcc, 0, v33, vcc
	v_add_co_u32_e32 v44, vcc, s73, v32
	s_nop 1
	v_addc_co_u32_e32 v45, vcc, 0, v33, vcc
	v_add_co_u32_e32 v46, vcc, s74, v32
	s_nop 1
	v_addc_co_u32_e32 v47, vcc, 0, v33, vcc
	v_add_co_u32_e32 v32, vcc, s75, v32
	s_nop 1
	v_addc_co_u32_e32 v33, vcc, 0, v33, vcc
	global_load_dword v34, v[34:35], off nt
	s_nop 0
	global_load_dword v35, v[36:37], off nt
	s_nop 0
	global_load_dword v36, v[38:39], off nt
	global_load_dword v37, v[40:41], off nt
	s_nop 0
	global_load_dword v38, v[42:43], off nt
	global_load_dword v39, v[44:45], off nt
	global_load_dword v40, v[46:47], off nt
	s_nop 0
	global_load_dword v32, v[32:33], off nt
	s_waitcnt vmcnt(30)
	ds_write2_b32 v14, v13, v31 offset1:66
	s_waitcnt vmcnt(28)
	ds_write2_b32 v14, v50, v51 offset0:132 offset1:198
	s_waitcnt vmcnt(26)
	ds_write2_b32 v24, v52, v53 offset0:8 offset1:74
	s_waitcnt vmcnt(24)
	ds_write2_b32 v24, v54, v55 offset0:140 offset1:206
	s_waitcnt vmcnt(22)
	ds_write2_b32 v25, v57, v58 offset0:16 offset1:82
	s_waitcnt vmcnt(20)
	ds_write2_b32 v25, v59, v60 offset0:148 offset1:214
	s_waitcnt vmcnt(18)
	ds_write2_b32 v26, v61, v62 offset0:24 offset1:90
	s_waitcnt vmcnt(16)
	ds_write2_b32 v26, v63, v64 offset0:156 offset1:222
	s_waitcnt vmcnt(14)
	ds_write2_b32 v27, v65, v66 offset0:32 offset1:98
	s_waitcnt vmcnt(12)
	ds_write2_b32 v27, v67, v68 offset0:164 offset1:230
	s_waitcnt vmcnt(10)
	ds_write2_b32 v28, v69, v70 offset0:40 offset1:106
	s_waitcnt vmcnt(8)
	ds_write2_b32 v28, v71, v48 offset0:172 offset1:238
	s_waitcnt vmcnt(6)
	ds_write2_b32 v29, v34, v35 offset0:48 offset1:114
	s_waitcnt vmcnt(4)
	ds_write2_b32 v29, v36, v37 offset0:180 offset1:246
	s_waitcnt vmcnt(2)
	ds_write2_b32 v30, v38, v39 offset0:56 offset1:122
	s_waitcnt vmcnt(0)
	ds_write2_b32 v30, v40, v32 offset0:188 offset1:254
	s_waitcnt lgkmcnt(0)
	ds_read2_b32 v[36:37], v16 offset0:33 offset1:41
	ds_read2_b32 v[38:39], v16 offset1:8
	ds_read2_b32 v[40:41], v16 offset0:66 offset1:74
	ds_read2_b32 v[42:43], v16 offset0:99 offset1:107
	ds_read2_b32 v[44:45], v16 offset0:132 offset1:140
	ds_read2_b32 v[46:47], v16 offset0:165 offset1:173
	ds_read2_b32 v[48:49], v16 offset0:198 offset1:206
	ds_read2_b32 v[50:51], v16 offset0:231 offset1:239
	v_mov_b32_e32 v13, v3
	v_lshl_add_u64 v[52:53], s[4:5], 0, v[12:13]
	v_or_b32_e32 v13, s2, v15
	v_lshlrev_b32_e32 v54, 11, v13
	v_mov_b32_e32 v55, v3
	s_waitcnt lgkmcnt(6)
	v_cvt_pk_bf16_f32 v32, v38, v36
	s_waitcnt lgkmcnt(4)
	v_cvt_pk_bf16_f32 v33, v40, v42
	s_waitcnt lgkmcnt(2)
	v_cvt_pk_bf16_f32 v34, v44, v46
	s_waitcnt lgkmcnt(0)
	v_cvt_pk_bf16_f32 v35, v48, v50
	v_lshl_add_u64 v[54:55], v[52:53], 0, v[54:55]
	global_store_dwordx4 v[54:55], v[32:35], off
	v_or_b32_e32 v13, s2, v17
	v_lshlrev_b32_e32 v36, 11, v13
	v_cvt_pk_bf16_f32 v32, v39, v37
	v_cvt_pk_bf16_f32 v33, v41, v43
	v_cvt_pk_bf16_f32 v34, v45, v47
	v_cvt_pk_bf16_f32 v35, v49, v51
	ds_read2_b32 v[38:39], v16 offset0:49 offset1:57
	ds_read2_b32 v[40:41], v16 offset0:16 offset1:24
	ds_read2_b32 v[42:43], v16 offset0:82 offset1:90
	ds_read2_b32 v[44:45], v16 offset0:115 offset1:123
	ds_read2_b32 v[46:47], v16 offset0:148 offset1:156
	ds_read2_b32 v[48:49], v16 offset0:181 offset1:189
	ds_read2_b32 v[50:51], v16 offset0:214 offset1:222
	ds_read2_b32 v[54:55], v16 offset0:247 offset1:255
	v_mov_b32_e32 v37, v3
	v_lshl_add_u64 v[36:37], v[52:53], 0, v[36:37]
	v_or_b32_e32 v13, s2, v18
	global_store_dwordx4 v[36:37], v[32:35], off
	v_lshlrev_b32_e32 v36, 11, v13
	v_mov_b32_e32 v37, v3
	s_waitcnt lgkmcnt(6)
	v_cvt_pk_bf16_f32 v32, v40, v38
	s_waitcnt lgkmcnt(4)
	v_cvt_pk_bf16_f32 v33, v42, v44
	s_waitcnt lgkmcnt(2)
	v_cvt_pk_bf16_f32 v34, v46, v48
	s_waitcnt lgkmcnt(0)
	v_cvt_pk_bf16_f32 v35, v50, v54
	v_lshl_add_u64 v[36:37], v[52:53], 0, v[36:37]
	v_or_b32_e32 v13, s2, v19
	global_store_dwordx4 v[36:37], v[32:35], off
	v_lshlrev_b32_e32 v36, 11, v13
	v_mov_b32_e32 v37, v3
	v_cvt_pk_bf16_f32 v32, v41, v39
	v_cvt_pk_bf16_f32 v33, v43, v45
	v_cvt_pk_bf16_f32 v34, v47, v49
	v_cvt_pk_bf16_f32 v35, v51, v55
	v_lshl_add_u64 v[36:37], v[52:53], 0, v[36:37]
	global_store_dwordx4 v[36:37], v[32:35], off
	s_waitcnt lgkmcnt(0)

.LBB0_12:
	s_andn2_b64 vcc, exec, s[4:5]
	s_cbranch_vccnz .LBB0_14
	s_lshl_b32 s2, s11, 5
	s_and_b32 s5, s2, 0xfffffc00
	s_load_dwordx2 s[96:97], s[0:1], 0x98
	s_add_i32 s4, s9, s93
	s_sub_i32 s95, s4, s5
	s_lshl_b32 s2, s6, 1
	s_add_i32 s98, s95, 0xfffe4000
	s_addk_i32 s2, 0x2400
	s_ashr_i32 s99, s98, 31
	s_andn2_b32 s2, s2, 63
	s_lshl_b64 s[98:99], s[98:99], 2
	s_waitcnt lgkmcnt(0)
	s_add_u32 s96, s96, s98
	v_or_b32_e32 v13, s2, v1
	s_addc_u32 s97, s97, s99
	v_lshl_add_u64 v[32:33], s[96:97], 0, v[2:3]
	v_lshlrev_b32_e32 v34, 10, v13
	v_mov_b32_e32 v35, v3
	v_lshl_add_u64 v[32:33], v[34:35], 2, v[32:33]
	v_add_co_u32_e32 v34, vcc, s14, v32
	v_subrev_u32_e32 v72, s5, v20
	s_nop 0
	v_addc_co_u32_e32 v35, vcc, 0, v33, vcc
	v_add_co_u32_e32 v36, vcc, s16, v32
	s_nop 1
	v_addc_co_u32_e32 v37, vcc, 0, v33, vcc
	v_add_co_u32_e32 v38, vcc, s17, v32
	s_nop 1
	v_addc_co_u32_e32 v39, vcc, 0, v33, vcc
	v_add_co_u32_e32 v40, vcc, s18, v32
	s_nop 1
	v_addc_co_u32_e32 v41, vcc, 0, v33, vcc
	v_add_co_u32_e32 v42, vcc, s19, v32
	s_nop 1
	v_addc_co_u32_e32 v43, vcc, 0, v33, vcc
	v_add_co_u32_e32 v44, vcc, s21, v32
	s_nop 1
	v_addc_co_u32_e32 v45, vcc, 0, v33, vcc
	v_add_co_u32_e32 v46, vcc, s23, v32
	s_nop 1
	v_addc_co_u32_e32 v47, vcc, 0, v33, vcc
	global_load_dword v13, v[32:33], off nt
	global_load_dword v31, v[34:35], off nt
	global_load_dword v50, v[36:37], off nt
	global_load_dword v51, v[38:39], off nt
	global_load_dword v52, v[40:41], off nt
	global_load_dword v53, v[42:43], off nt
	global_load_dword v54, v[44:45], off nt
	global_load_dword v55, v[46:47], off nt
	v_add_co_u32_e32 v34, vcc, s26, v32
	s_nop 1
	v_addc_co_u32_e32 v35, vcc, 0, v33, vcc
	v_add_co_u32_e32 v36, vcc, s27, v32
	s_nop 1
	v_addc_co_u32_e32 v37, vcc, 0, v33, vcc
	v_add_co_u32_e32 v38, vcc, s28, v32
	s_nop 1
	v_addc_co_u32_e32 v39, vcc, 0, v33, vcc
	v_add_co_u32_e32 v40, vcc, s29, v32
	s_nop 1
	v_addc_co_u32_e32 v41, vcc, 0, v33, vcc
	v_add_co_u32_e32 v42, vcc, s30, v32
	s_nop 1
	v_addc_co_u32_e32 v43, vcc, 0, v33, vcc
	v_add_co_u32_e32 v44, vcc, s31, v32
	s_nop 1
	v_addc_co_u32_e32 v45, vcc, 0, v33, vcc
	v_add_co_u32_e32 v46, vcc, s33, v32
	s_nop 1
	v_addc_co_u32_e32 v47, vcc, 0, v33, vcc
	v_add_co_u32_e32 v48, vcc, s34, v32
	s_nop 1
	v_addc_co_u32_e32 v49, vcc, 0, v33, vcc
	global_load_dword v57, v[34:35], off nt
	global_load_dword v58, v[36:37], off nt
	global_load_dword v59, v[38:39], off nt
	global_load_dword v60, v[40:41], off nt
	global_load_dword v61, v[42:43], off nt
	global_load_dword v62, v[44:45], off nt
	global_load_dword v63, v[46:47], off nt
	global_load_dword v64, v[48:49], off nt
	v_add_co_u32_e32 v34, vcc, s35, v32
	s_nop 1
	v_addc_co_u32_e32 v35, vcc, 0, v33, vcc
	v_add_co_u32_e32 v36, vcc, s36, v32
	s_nop 1
	v_addc_co_u32_e32 v37, vcc, 0, v33, vcc
	v_add_co_u32_e32 v38, vcc, s37, v32
	s_nop 1
	v_addc_co_u32_e32 v39, vcc, 0, v33, vcc
	v_add_co_u32_e32 v40, vcc, s38, v32
	s_nop 1
	v_addc_co_u32_e32 v41, vcc, 0, v33, vcc
	v_add_co_u32_e32 v42, vcc, s39, v32
	s_nop 1
	v_addc_co_u32_e32 v43, vcc, 0, v33, vcc
	v_add_co_u32_e32 v44, vcc, s40, v32
	s_nop 1
	v_addc_co_u32_e32 v45, vcc, 0, v33, vcc
	v_add_co_u32_e32 v46, vcc, s41, v32
	s_nop 1
	v_addc_co_u32_e32 v47, vcc, 0, v33, vcc
	v_add_co_u32_e32 v48, vcc, s42, v32
	s_nop 1
	v_addc_co_u32_e32 v49, vcc, 0, v33, vcc
	global_load_dword v65, v[34:35], off nt
	global_load_dword v66, v[36:37], off nt
	global_load_dword v67, v[38:39], off nt
	global_load_dword v68, v[40:41], off nt
	global_load_dword v69, v[42:43], off nt
	global_load_dword v70, v[44:45], off nt
	global_load_dword v71, v[46:47], off nt
	s_nop 0
	global_load_dword v48, v[48:49], off nt
	v_add_co_u32_e32 v34, vcc, s43, v32
	s_nop 1
	v_addc_co_u32_e32 v35, vcc, 0, v33, vcc
	v_add_co_u32_e32 v36, vcc, s44, v32
	s_nop 1
	v_addc_co_u32_e32 v37, vcc, 0, v33, vcc
	v_add_co_u32_e32 v38, vcc, s45, v32
	s_nop 1
	v_addc_co_u32_e32 v39, vcc, 0, v33, vcc
	v_add_co_u32_e32 v40, vcc, s46, v32
	s_nop 1
	v_addc_co_u32_e32 v41, vcc, 0, v33, vcc
	v_add_co_u32_e32 v42, vcc, s47, v32
	s_nop 1
	v_addc_co_u32_e32 v43, vcc, 0, v33, vcc
	v_add_co_u32_e32 v44, vcc, s48, v32
	s_nop 1
	v_addc_co_u32_e32 v45, vcc, 0, v33, vcc
	v_add_co_u32_e32 v46, vcc, s49, v32
	s_nop 1
	v_addc_co_u32_e32 v47, vcc, 0, v33, vcc
	v_add_co_u32_e32 v32, vcc, s50, v32
	s_nop 1
	v_addc_co_u32_e32 v33, vcc, 0, v33, vcc
	global_load_dword v34, v[34:35], off nt
	s_nop 0
	global_load_dword v35, v[36:37], off nt
	s_nop 0
	global_load_dword v36, v[38:39], off nt
	global_load_dword v37, v[40:41], off nt
	s_nop 0
	global_load_dword v38, v[42:43], off nt
	global_load_dword v39, v[44:45], off nt
	global_load_dword v40, v[46:47], off nt
	s_nop 0
	global_load_dword v32, v[32:33], off nt
	s_waitcnt vmcnt(30)
	ds_write2_b32 v14, v13, v31 offset1:66
	s_waitcnt vmcnt(28)
	ds_write2_b32 v14, v50, v51 offset0:132 offset1:198
	s_waitcnt vmcnt(26)
	ds_write2_b32 v24, v52, v53 offset0:8 offset1:74
	s_waitcnt vmcnt(24)
	ds_write2_b32 v24, v54, v55 offset0:140 offset1:206
	s_waitcnt vmcnt(22)
	ds_write2_b32 v25, v57, v58 offset0:16 offset1:82
	s_waitcnt vmcnt(20)
	ds_write2_b32 v25, v59, v60 offset0:148 offset1:214
	s_waitcnt vmcnt(18)
	ds_write2_b32 v26, v61, v62 offset0:24 offset1:90
	s_waitcnt vmcnt(16)
	ds_write2_b32 v26, v63, v64 offset0:156 offset1:222
	s_waitcnt vmcnt(14)
	ds_write2_b32 v27, v65, v66 offset0:32 offset1:98
	s_waitcnt vmcnt(12)
	ds_write2_b32 v27, v67, v68 offset0:164 offset1:230
	s_waitcnt vmcnt(10)
	ds_write2_b32 v28, v69, v70 offset0:40 offset1:106
	s_waitcnt vmcnt(8)
	ds_write2_b32 v28, v71, v48 offset0:172 offset1:238
	s_waitcnt vmcnt(6)
	ds_write2_b32 v29, v34, v35 offset0:48 offset1:114
	s_waitcnt vmcnt(4)
	ds_write2_b32 v29, v36, v37 offset0:180 offset1:246
	s_waitcnt vmcnt(2)
	ds_write2_b32 v30, v38, v39 offset0:56 offset1:122
	s_waitcnt vmcnt(0)
	ds_write2_b32 v30, v40, v32 offset0:188 offset1:254
	s_waitcnt lgkmcnt(0)
	ds_read2_b32 v[36:37], v16 offset0:33 offset1:41
	ds_read2_b32 v[38:39], v16 offset1:8
	ds_read2_b32 v[40:41], v16 offset0:66 offset1:74
	ds_read2_b32 v[42:43], v16 offset0:99 offset1:107
	ds_read2_b32 v[44:45], v16 offset0:132 offset1:140
	ds_read2_b32 v[46:47], v16 offset0:165 offset1:173
	ds_read2_b32 v[48:49], v16 offset0:198 offset1:206
	ds_read2_b32 v[50:51], v16 offset0:231 offset1:239
	s_waitcnt lgkmcnt(6)
	v_cvt_pk_bf16_f32 v32, v38, v36
	v_add_u32_e32 v36, s4, v72
	v_add_u32_e32 v54, -16, v36
	v_ashrrev_i32_e32 v55, 31, v54
	v_lshl_add_u64 v[52:53], s[2:3], 1, v[4:5]
	v_lshlrev_b64 v[54:55], 11, v[54:55]
	s_waitcnt lgkmcnt(4)
	v_cvt_pk_bf16_f32 v33, v40, v42
	s_waitcnt lgkmcnt(2)
	v_cvt_pk_bf16_f32 v34, v44, v46
	s_waitcnt lgkmcnt(0)
	v_cvt_pk_bf16_f32 v35, v48, v50
	v_lshl_add_u64 v[54:55], v[52:53], 0, v[54:55]
	global_store_dwordx4 v[54:55], v[32:35], off
	v_add_u32_e32 v38, -8, v36
	s_nop 0
	v_cvt_pk_bf16_f32 v32, v39, v37
	v_cvt_pk_bf16_f32 v33, v41, v43
	v_cvt_pk_bf16_f32 v34, v45, v47
	v_cvt_pk_bf16_f32 v35, v49, v51
	v_ashrrev_i32_e32 v39, 31, v38
	ds_read2_b32 v[40:41], v16 offset0:49 offset1:57
	ds_read2_b32 v[42:43], v16 offset0:16 offset1:24
	ds_read2_b32 v[44:45], v16 offset0:82 offset1:90
	ds_read2_b32 v[46:47], v16 offset0:115 offset1:123
	ds_read2_b32 v[48:49], v16 offset0:148 offset1:156
	ds_read2_b32 v[50:51], v16 offset0:181 offset1:189
	ds_read2_b32 v[54:55], v16 offset0:214 offset1:222
	ds_read2_b32 v[58:59], v16 offset0:247 offset1:255
	v_lshlrev_b64 v[38:39], 11, v[38:39]
	v_lshl_add_u64 v[38:39], v[52:53], 0, v[38:39]
	v_ashrrev_i32_e32 v37, 31, v36
	global_store_dwordx4 v[38:39], v[32:35], off
	v_lshlrev_b64 v[38:39], 11, v[36:37]
	v_add_u32_e32 v36, 8, v36
	v_ashrrev_i32_e32 v37, 31, v36
	s_waitcnt lgkmcnt(6)
	v_cvt_pk_bf16_f32 v32, v42, v40
	s_waitcnt lgkmcnt(4)
	v_cvt_pk_bf16_f32 v33, v44, v46
	s_waitcnt lgkmcnt(2)
	v_cvt_pk_bf16_f32 v34, v48, v50
	s_waitcnt lgkmcnt(0)
	v_cvt_pk_bf16_f32 v35, v54, v58
	v_lshl_add_u64 v[38:39], v[52:53], 0, v[38:39]
	v_lshlrev_b64 v[36:37], 11, v[36:37]
	global_store_dwordx4 v[38:39], v[32:35], off
	v_lshl_add_u64 v[36:37], v[52:53], 0, v[36:37]
	s_nop 0
	v_cvt_pk_bf16_f32 v32, v43, v41
	v_cvt_pk_bf16_f32 v33, v45, v47
	v_cvt_pk_bf16_f32 v34, v49, v51
	v_cvt_pk_bf16_f32 v35, v55, v59
	global_store_dwordx4 v[36:37], v[32:35], off
	s_waitcnt lgkmcnt(0)

.LBB0_15:
	s_andn2_b64 vcc, exec, s[4:5]
	s_cbranch_vccnz .LBB0_17
	s_lshl_b32 s2, s12, 5
	s_and_b32 s4, s2, 0xfffffc00
	s_sub_i32 s5, s9, s4
	s_load_dwordx2 s[96:97], s[0:1], 0x80
	s_add_i32 s5, s93, s5
	s_lshl_b32 s2, s6, 1
	s_add_i32 s98, s5, 0xfffe8000
	s_addk_i32 s2, 0x2800
	s_ashr_i32 s99, s98, 31
	s_andn2_b32 s2, s2, 63
	s_lshl_b64 s[98:99], s[98:99], 2
	s_waitcnt lgkmcnt(0)
	s_add_u32 s96, s96, s98
	v_or_b32_e32 v13, s2, v1
	s_addc_u32 s97, s97, s99
	v_lshl_add_u64 v[32:33], s[96:97], 0, v[2:3]
	v_lshlrev_b32_e32 v34, 10, v13
	v_mov_b32_e32 v35, v3
	v_lshl_add_u64 v[32:33], v[34:35], 2, v[32:33]
	v_add_co_u32_e32 v34, vcc, s14, v32
	v_subrev_u32_e32 v72, s4, v21
	s_nop 0
	v_addc_co_u32_e32 v35, vcc, 0, v33, vcc
	v_add_co_u32_e32 v36, vcc, s16, v32
	s_nop 1
	v_addc_co_u32_e32 v37, vcc, 0, v33, vcc
	v_add_co_u32_e32 v38, vcc, s17, v32
	s_nop 1
	v_addc_co_u32_e32 v39, vcc, 0, v33, vcc
	v_add_co_u32_e32 v40, vcc, s18, v32
	s_nop 1
	v_addc_co_u32_e32 v41, vcc, 0, v33, vcc
	v_add_co_u32_e32 v42, vcc, s19, v32
	s_nop 1
	v_addc_co_u32_e32 v43, vcc, 0, v33, vcc
	v_add_co_u32_e32 v44, vcc, s21, v32
	s_nop 1
	v_addc_co_u32_e32 v45, vcc, 0, v33, vcc
	v_add_co_u32_e32 v46, vcc, s23, v32
	s_nop 1
	v_addc_co_u32_e32 v47, vcc, 0, v33, vcc
	global_load_dword v13, v[32:33], off nt
	global_load_dword v31, v[34:35], off nt
	global_load_dword v50, v[36:37], off nt
	global_load_dword v51, v[38:39], off nt
	global_load_dword v52, v[40:41], off nt
	global_load_dword v53, v[42:43], off nt
	global_load_dword v54, v[44:45], off nt
	global_load_dword v55, v[46:47], off nt
	v_add_co_u32_e32 v34, vcc, s26, v32
	s_nop 1
	v_addc_co_u32_e32 v35, vcc, 0, v33, vcc
	v_add_co_u32_e32 v36, vcc, s27, v32
	s_nop 1
	v_addc_co_u32_e32 v37, vcc, 0, v33, vcc
	v_add_co_u32_e32 v38, vcc, s28, v32
	s_nop 1
	v_addc_co_u32_e32 v39, vcc, 0, v33, vcc
	v_add_co_u32_e32 v40, vcc, s29, v32
	s_nop 1
	v_addc_co_u32_e32 v41, vcc, 0, v33, vcc
	v_add_co_u32_e32 v42, vcc, s30, v32
	s_nop 1
	v_addc_co_u32_e32 v43, vcc, 0, v33, vcc
	v_add_co_u32_e32 v44, vcc, s31, v32
	s_nop 1
	v_addc_co_u32_e32 v45, vcc, 0, v33, vcc
	v_add_co_u32_e32 v46, vcc, s33, v32
	s_nop 1
	v_addc_co_u32_e32 v47, vcc, 0, v33, vcc
	v_add_co_u32_e32 v48, vcc, s34, v32
	s_nop 1
	v_addc_co_u32_e32 v49, vcc, 0, v33, vcc
	global_load_dword v57, v[34:35], off nt
	global_load_dword v58, v[36:37], off nt
	global_load_dword v59, v[38:39], off nt
	global_load_dword v60, v[40:41], off nt
	global_load_dword v61, v[42:43], off nt
	global_load_dword v62, v[44:45], off nt
	global_load_dword v63, v[46:47], off nt
	global_load_dword v64, v[48:49], off nt
	v_add_co_u32_e32 v34, vcc, s35, v32
	s_nop 1
	v_addc_co_u32_e32 v35, vcc, 0, v33, vcc
	v_add_co_u32_e32 v36, vcc, s36, v32
	s_nop 1
	v_addc_co_u32_e32 v37, vcc, 0, v33, vcc
	v_add_co_u32_e32 v38, vcc, s37, v32
	s_nop 1
	v_addc_co_u32_e32 v39, vcc, 0, v33, vcc
	v_add_co_u32_e32 v40, vcc, s38, v32
	s_nop 1
	v_addc_co_u32_e32 v41, vcc, 0, v33, vcc
	v_add_co_u32_e32 v42, vcc, s39, v32
	s_nop 1
	v_addc_co_u32_e32 v43, vcc, 0, v33, vcc
	v_add_co_u32_e32 v44, vcc, s40, v32
	s_nop 1
	v_addc_co_u32_e32 v45, vcc, 0, v33, vcc
	v_add_co_u32_e32 v46, vcc, s41, v32
	s_nop 1
	v_addc_co_u32_e32 v47, vcc, 0, v33, vcc
	v_add_co_u32_e32 v48, vcc, s42, v32
	s_nop 1
	v_addc_co_u32_e32 v49, vcc, 0, v33, vcc
	global_load_dword v65, v[34:35], off nt
	global_load_dword v66, v[36:37], off nt
	global_load_dword v67, v[38:39], off nt
	global_load_dword v68, v[40:41], off nt
	global_load_dword v69, v[42:43], off nt
	global_load_dword v70, v[44:45], off nt
	global_load_dword v71, v[46:47], off nt
	s_nop 0
	global_load_dword v48, v[48:49], off nt
	v_add_co_u32_e32 v34, vcc, s43, v32
	s_nop 1
	v_addc_co_u32_e32 v35, vcc, 0, v33, vcc
	v_add_co_u32_e32 v36, vcc, s44, v32
	s_nop 1
	v_addc_co_u32_e32 v37, vcc, 0, v33, vcc
	v_add_co_u32_e32 v38, vcc, s45, v32
	s_nop 1
	v_addc_co_u32_e32 v39, vcc, 0, v33, vcc
	v_add_co_u32_e32 v40, vcc, s46, v32
	s_nop 1
	v_addc_co_u32_e32 v41, vcc, 0, v33, vcc
	v_add_co_u32_e32 v42, vcc, s47, v32
	s_nop 1
	v_addc_co_u32_e32 v43, vcc, 0, v33, vcc
	v_add_co_u32_e32 v44, vcc, s48, v32
	s_nop 1
	v_addc_co_u32_e32 v45, vcc, 0, v33, vcc
	v_add_co_u32_e32 v46, vcc, s49, v32
	s_nop 1
	v_addc_co_u32_e32 v47, vcc, 0, v33, vcc
	v_add_co_u32_e32 v32, vcc, s50, v32
	s_nop 1
	v_addc_co_u32_e32 v33, vcc, 0, v33, vcc
	global_load_dword v34, v[34:35], off nt
	s_nop 0
	global_load_dword v35, v[36:37], off nt
	s_nop 0
	global_load_dword v36, v[38:39], off nt
	global_load_dword v37, v[40:41], off nt
	s_nop 0
	global_load_dword v38, v[42:43], off nt
	global_load_dword v39, v[44:45], off nt
	global_load_dword v40, v[46:47], off nt
	s_nop 0
	global_load_dword v32, v[32:33], off nt
	s_waitcnt vmcnt(30)
	ds_write2_b32 v14, v13, v31 offset1:66
	s_waitcnt vmcnt(28)
	ds_write2_b32 v14, v50, v51 offset0:132 offset1:198
	s_waitcnt vmcnt(26)
	ds_write2_b32 v24, v52, v53 offset0:8 offset1:74
	s_waitcnt vmcnt(24)
	ds_write2_b32 v24, v54, v55 offset0:140 offset1:206
	s_waitcnt vmcnt(22)
	ds_write2_b32 v25, v57, v58 offset0:16 offset1:82
	s_waitcnt vmcnt(20)
	ds_write2_b32 v25, v59, v60 offset0:148 offset1:214
	s_waitcnt vmcnt(18)
	ds_write2_b32 v26, v61, v62 offset0:24 offset1:90
	s_waitcnt vmcnt(16)
	ds_write2_b32 v26, v63, v64 offset0:156 offset1:222
	s_waitcnt vmcnt(14)
	ds_write2_b32 v27, v65, v66 offset0:32 offset1:98
	s_waitcnt vmcnt(12)
	ds_write2_b32 v27, v67, v68 offset0:164 offset1:230
	s_waitcnt vmcnt(10)
	ds_write2_b32 v28, v69, v70 offset0:40 offset1:106
	s_waitcnt vmcnt(8)
	ds_write2_b32 v28, v71, v48 offset0:172 offset1:238
	s_waitcnt vmcnt(6)
	ds_write2_b32 v29, v34, v35 offset0:48 offset1:114
	s_waitcnt vmcnt(4)
	ds_write2_b32 v29, v36, v37 offset0:180 offset1:246
	s_waitcnt vmcnt(2)
	ds_write2_b32 v30, v38, v39 offset0:56 offset1:122
	s_waitcnt vmcnt(0)
	ds_write2_b32 v30, v40, v32 offset0:188 offset1:254
	s_waitcnt lgkmcnt(0)
	ds_read2_b32 v[36:37], v16 offset0:33 offset1:41
	ds_read2_b32 v[38:39], v16 offset1:8
	ds_read2_b32 v[40:41], v16 offset0:66 offset1:74
	ds_read2_b32 v[42:43], v16 offset0:99 offset1:107
	ds_read2_b32 v[44:45], v16 offset0:132 offset1:140
	ds_read2_b32 v[46:47], v16 offset0:165 offset1:173
	ds_read2_b32 v[48:49], v16 offset0:198 offset1:206
	ds_read2_b32 v[50:51], v16 offset0:231 offset1:239
	v_lshl_add_u64 v[52:53], s[2:3], 1, v[6:7]
	s_add_i32 s2, s9, s93
	s_waitcnt lgkmcnt(6)
	v_cvt_pk_bf16_f32 v32, v38, v36
	v_add_u32_e32 v36, s2, v72
	v_add_u32_e32 v54, -16, v36
	v_ashrrev_i32_e32 v55, 31, v54
	v_lshlrev_b64 v[54:55], 11, v[54:55]
	s_waitcnt lgkmcnt(4)
	v_cvt_pk_bf16_f32 v33, v40, v42
	s_waitcnt lgkmcnt(2)
	v_cvt_pk_bf16_f32 v34, v44, v46
	s_waitcnt lgkmcnt(0)
	v_cvt_pk_bf16_f32 v35, v48, v50
	v_lshl_add_u64 v[54:55], v[52:53], 0, v[54:55]
	global_store_dwordx4 v[54:55], v[32:35], off
	v_add_u32_e32 v38, -8, v36
	s_nop 0
	v_cvt_pk_bf16_f32 v32, v39, v37
	v_cvt_pk_bf16_f32 v33, v41, v43
	v_cvt_pk_bf16_f32 v34, v45, v47
	v_cvt_pk_bf16_f32 v35, v49, v51
	v_ashrrev_i32_e32 v39, 31, v38
	ds_read2_b32 v[40:41], v16 offset0:49 offset1:57
	ds_read2_b32 v[42:43], v16 offset0:16 offset1:24
	ds_read2_b32 v[44:45], v16 offset0:82 offset1:90
	ds_read2_b32 v[46:47], v16 offset0:115 offset1:123
	ds_read2_b32 v[48:49], v16 offset0:148 offset1:156
	ds_read2_b32 v[50:51], v16 offset0:181 offset1:189
	ds_read2_b32 v[54:55], v16 offset0:214 offset1:222
	ds_read2_b32 v[58:59], v16 offset0:247 offset1:255
	v_lshlrev_b64 v[38:39], 11, v[38:39]
	v_lshl_add_u64 v[38:39], v[52:53], 0, v[38:39]
	v_ashrrev_i32_e32 v37, 31, v36
	global_store_dwordx4 v[38:39], v[32:35], off
	v_lshlrev_b64 v[38:39], 11, v[36:37]
	v_add_u32_e32 v36, 8, v36
	v_ashrrev_i32_e32 v37, 31, v36
	s_waitcnt lgkmcnt(6)
	v_cvt_pk_bf16_f32 v32, v42, v40
	s_waitcnt lgkmcnt(4)
	v_cvt_pk_bf16_f32 v33, v44, v46
	s_waitcnt lgkmcnt(2)
	v_cvt_pk_bf16_f32 v34, v48, v50
	s_waitcnt lgkmcnt(0)
	v_cvt_pk_bf16_f32 v35, v54, v58
	v_lshl_add_u64 v[38:39], v[52:53], 0, v[38:39]
	v_lshlrev_b64 v[36:37], 11, v[36:37]
	global_store_dwordx4 v[38:39], v[32:35], off
	v_lshl_add_u64 v[36:37], v[52:53], 0, v[36:37]
	s_nop 0
	v_cvt_pk_bf16_f32 v32, v43, v41
	v_cvt_pk_bf16_f32 v33, v45, v47
	v_cvt_pk_bf16_f32 v34, v49, v51
	v_cvt_pk_bf16_f32 v35, v55, v59
	global_store_dwordx4 v[36:37], v[32:35], off
	s_waitcnt lgkmcnt(0)

.LBB0_18:
	s_andn2_b64 vcc, exec, s[4:5]
	s_cbranch_vccnz .LBB0_20
	s_and_b32 s2, 0xffff, s13
	s_mul_hi_u32 s5, s2, 0x2aaaaab
	s_mulk_i32 s5, 0xc00
	s_load_dwordx2 s[96:97], s[0:1], 0x88
	s_add_i32 s4, s9, s93
	s_sub_i32 s95, s4, s5
	s_mul_i32 s2, s6, 0xaaab
	s_add_i32 s98, s95, 0xffff4000
	s_add_i32 s2, s2, 0x11555e00
	s_ashr_i32 s99, s98, 31
	s_lshr_b32 s2, s2, 22
	s_lshl_b64 s[98:99], s[98:99], 2
	v_lshl_or_b32 v13, s2, 6, v1
	s_waitcnt lgkmcnt(0)
	s_add_u32 s96, s96, s98
	s_addc_u32 s97, s97, s99
	v_mul_u32_u24_e32 v13, 0xc00, v13
	v_lshl_add_u64 v[32:33], s[96:97], 0, v[2:3]
	v_lshlrev_b32_e32 v34, 2, v13
	v_mov_b32_e32 v35, v3
	v_lshl_add_u64 v[32:33], v[32:33], 0, v[34:35]
	v_add_co_u32_e32 v34, vcc, s17, v32
	v_subrev_u32_e32 v72, s5, v22
	s_nop 0
	v_addc_co_u32_e32 v35, vcc, 0, v33, vcc
	v_add_co_u32_e32 v36, vcc, s21, v32
	s_lshl_b32 s2, s2, 7
	s_nop 0
	v_addc_co_u32_e32 v37, vcc, 0, v33, vcc
	v_add_co_u32_e32 v38, vcc, s27, v32
	s_nop 1
	v_addc_co_u32_e32 v39, vcc, 0, v33, vcc
	v_add_co_u32_e32 v40, vcc, s30, v32
	s_nop 1
	v_addc_co_u32_e32 v41, vcc, 0, v33, vcc
	v_add_co_u32_e32 v42, vcc, s34, v32
	s_nop 1
	v_addc_co_u32_e32 v43, vcc, 0, v33, vcc
	v_add_co_u32_e32 v44, vcc, s37, v32
	s_nop 1
	v_addc_co_u32_e32 v45, vcc, 0, v33, vcc
	v_add_co_u32_e32 v46, vcc, s40, v32
	s_nop 1
	v_addc_co_u32_e32 v47, vcc, 0, v33, vcc
	global_load_dword v13, v[32:33], off nt
	global_load_dword v31, v[34:35], off nt
	global_load_dword v50, v[36:37], off nt
	global_load_dword v51, v[38:39], off nt
	global_load_dword v52, v[40:41], off nt
	global_load_dword v53, v[42:43], off nt
	global_load_dword v54, v[44:45], off nt
	global_load_dword v55, v[46:47], off nt
	v_add_co_u32_e32 v34, vcc, s43, v32
	s_nop 1
	v_addc_co_u32_e32 v35, vcc, 0, v33, vcc
	v_add_co_u32_e32 v36, vcc, s46, v32
	s_nop 1
	v_addc_co_u32_e32 v37, vcc, 0, v33, vcc
	v_add_co_u32_e32 v38, vcc, s49, v32
	s_nop 1
	v_addc_co_u32_e32 v39, vcc, 0, v33, vcc
	v_add_co_u32_e32 v40, vcc, s76, v32
	s_nop 1
	v_addc_co_u32_e32 v41, vcc, 0, v33, vcc
	v_add_co_u32_e32 v42, vcc, s53, v32
	s_nop 1
	v_addc_co_u32_e32 v43, vcc, 0, v33, vcc
	v_add_co_u32_e32 v44, vcc, s77, v32
	s_nop 1
	v_addc_co_u32_e32 v45, vcc, 0, v33, vcc
	v_add_co_u32_e32 v46, vcc, s78, v32
	s_nop 1
	v_addc_co_u32_e32 v47, vcc, 0, v33, vcc
	v_add_co_u32_e32 v48, vcc, s79, v32
	s_nop 1
	v_addc_co_u32_e32 v49, vcc, 0, v33, vcc
	global_load_dword v57, v[34:35], off nt
	global_load_dword v58, v[36:37], off nt
	global_load_dword v59, v[38:39], off nt
	global_load_dword v60, v[40:41], off nt
	global_load_dword v61, v[42:43], off nt
	global_load_dword v62, v[44:45], off nt
	global_load_dword v63, v[46:47], off nt
	global_load_dword v64, v[48:49], off nt
	v_add_co_u32_e32 v34, vcc, s56, v32
	s_nop 1
	v_addc_co_u32_e32 v35, vcc, 0, v33, vcc
	v_add_co_u32_e32 v36, vcc, s80, v32
	s_nop 1
	v_addc_co_u32_e32 v37, vcc, 0, v33, vcc
	v_add_co_u32_e32 v38, vcc, s81, v32
	s_nop 1
	v_addc_co_u32_e32 v39, vcc, 0, v33, vcc
	v_add_co_u32_e32 v40, vcc, s82, v32
	s_nop 1
	v_addc_co_u32_e32 v41, vcc, 0, v33, vcc
	v_add_co_u32_e32 v42, vcc, s59, v32
	s_nop 1
	v_addc_co_u32_e32 v43, vcc, 0, v33, vcc
	v_add_co_u32_e32 v44, vcc, s83, v32
	s_nop 1
	v_addc_co_u32_e32 v45, vcc, 0, v33, vcc
	v_add_co_u32_e32 v46, vcc, s84, v32
	s_nop 1
	v_addc_co_u32_e32 v47, vcc, 0, v33, vcc
	v_add_co_u32_e32 v48, vcc, s85, v32
	s_nop 1
	v_addc_co_u32_e32 v49, vcc, 0, v33, vcc
	global_load_dword v65, v[34:35], off nt
	global_load_dword v66, v[36:37], off nt
	global_load_dword v67, v[38:39], off nt
	global_load_dword v68, v[40:41], off nt
	global_load_dword v69, v[42:43], off nt
	global_load_dword v70, v[44:45], off nt
	global_load_dword v71, v[46:47], off nt
	s_nop 0
	global_load_dword v48, v[48:49], off nt
	v_add_co_u32_e32 v34, vcc, s62, v32
	s_nop 1
	v_addc_co_u32_e32 v35, vcc, 0, v33, vcc
	v_add_co_u32_e32 v36, vcc, s86, v32
	s_nop 1
	v_addc_co_u32_e32 v37, vcc, 0, v33, vcc
	v_add_co_u32_e32 v38, vcc, s87, v32
	s_nop 1
	v_addc_co_u32_e32 v39, vcc, 0, v33, vcc
	v_add_co_u32_e32 v40, vcc, s88, v32
	s_nop 1
	v_addc_co_u32_e32 v41, vcc, 0, v33, vcc
	v_add_co_u32_e32 v42, vcc, s65, v32
	s_nop 1
	v_addc_co_u32_e32 v43, vcc, 0, v33, vcc
	v_add_co_u32_e32 v44, vcc, s89, v32
	s_nop 1
	v_addc_co_u32_e32 v45, vcc, 0, v33, vcc
	v_add_co_u32_e32 v46, vcc, s90, v32
	s_nop 1
	v_addc_co_u32_e32 v47, vcc, 0, v33, vcc
	v_add_co_u32_e32 v32, vcc, s91, v32
	s_nop 1
	v_addc_co_u32_e32 v33, vcc, 0, v33, vcc
	global_load_dword v34, v[34:35], off nt
	s_nop 0
	global_load_dword v35, v[36:37], off nt
	s_nop 0
	global_load_dword v36, v[38:39], off nt
	global_load_dword v37, v[40:41], off nt
	s_nop 0
	global_load_dword v38, v[42:43], off nt
	global_load_dword v39, v[44:45], off nt
	global_load_dword v40, v[46:47], off nt
	s_nop 0
	global_load_dword v32, v[32:33], off nt
	s_waitcnt vmcnt(30)
	ds_write2_b32 v14, v13, v31 offset1:66
	s_waitcnt vmcnt(28)
	ds_write2_b32 v14, v50, v51 offset0:132 offset1:198
	s_waitcnt vmcnt(26)
	ds_write2_b32 v24, v52, v53 offset0:8 offset1:74
	s_waitcnt vmcnt(24)
	ds_write2_b32 v24, v54, v55 offset0:140 offset1:206
	s_waitcnt vmcnt(22)
	ds_write2_b32 v25, v57, v58 offset0:16 offset1:82
	s_waitcnt vmcnt(20)
	ds_write2_b32 v25, v59, v60 offset0:148 offset1:214
	s_waitcnt vmcnt(18)
	ds_write2_b32 v26, v61, v62 offset0:24 offset1:90
	s_waitcnt vmcnt(16)
	ds_write2_b32 v26, v63, v64 offset0:156 offset1:222
	s_waitcnt vmcnt(14)
	ds_write2_b32 v27, v65, v66 offset0:32 offset1:98
	s_waitcnt vmcnt(12)
	ds_write2_b32 v27, v67, v68 offset0:164 offset1:230
	s_waitcnt vmcnt(10)
	ds_write2_b32 v28, v69, v70 offset0:40 offset1:106
	s_waitcnt vmcnt(8)
	ds_write2_b32 v28, v71, v48 offset0:172 offset1:238
	s_waitcnt vmcnt(6)
	ds_write2_b32 v29, v34, v35 offset0:48 offset1:114
	s_waitcnt vmcnt(4)
	ds_write2_b32 v29, v36, v37 offset0:180 offset1:246
	s_waitcnt vmcnt(2)
	ds_write2_b32 v30, v38, v39 offset0:56 offset1:122
	s_waitcnt vmcnt(0)
	ds_write2_b32 v30, v40, v32 offset0:188 offset1:254
	s_waitcnt lgkmcnt(0)
	ds_read2_b32 v[36:37], v16 offset0:33 offset1:41
	ds_read2_b32 v[38:39], v16 offset1:8
	ds_read2_b32 v[40:41], v16 offset0:66 offset1:74
	ds_read2_b32 v[42:43], v16 offset0:99 offset1:107
	ds_read2_b32 v[44:45], v16 offset0:132 offset1:140
	ds_read2_b32 v[46:47], v16 offset0:165 offset1:173
	ds_read2_b32 v[48:49], v16 offset0:198 offset1:206
	ds_read2_b32 v[50:51], v16 offset0:231 offset1:239
	s_waitcnt lgkmcnt(6)
	v_cvt_pk_bf16_f32 v32, v38, v36
	v_add_u32_e32 v36, s4, v72
	v_add_u32_e32 v54, -16, v36
	v_ashrrev_i32_e32 v55, 31, v54
	v_lshl_add_u64 v[52:53], v[8:9], 0, s[2:3]
	v_lshlrev_b64 v[54:55], 11, v[54:55]
	s_waitcnt lgkmcnt(4)
	v_cvt_pk_bf16_f32 v33, v40, v42
	s_waitcnt lgkmcnt(2)
	v_cvt_pk_bf16_f32 v34, v44, v46
	s_waitcnt lgkmcnt(0)
	v_cvt_pk_bf16_f32 v35, v48, v50
	v_lshl_add_u64 v[54:55], v[52:53], 0, v[54:55]
	global_store_dwordx4 v[54:55], v[32:35], off
	v_add_u32_e32 v38, -8, v36
	s_nop 0
	v_cvt_pk_bf16_f32 v32, v39, v37
	v_cvt_pk_bf16_f32 v33, v41, v43
	v_cvt_pk_bf16_f32 v34, v45, v47
	v_cvt_pk_bf16_f32 v35, v49, v51
	v_ashrrev_i32_e32 v39, 31, v38
	ds_read2_b32 v[40:41], v16 offset0:49 offset1:57
	ds_read2_b32 v[42:43], v16 offset0:16 offset1:24
	ds_read2_b32 v[44:45], v16 offset0:82 offset1:90
	ds_read2_b32 v[46:47], v16 offset0:115 offset1:123
	ds_read2_b32 v[48:49], v16 offset0:148 offset1:156
	ds_read2_b32 v[50:51], v16 offset0:181 offset1:189
	ds_read2_b32 v[54:55], v16 offset0:214 offset1:222
	ds_read2_b32 v[58:59], v16 offset0:247 offset1:255
	v_lshlrev_b64 v[38:39], 11, v[38:39]
	v_lshl_add_u64 v[38:39], v[52:53], 0, v[38:39]
	v_ashrrev_i32_e32 v37, 31, v36
	global_store_dwordx4 v[38:39], v[32:35], off
	v_lshlrev_b64 v[38:39], 11, v[36:37]
	v_add_u32_e32 v36, 8, v36
	v_ashrrev_i32_e32 v37, 31, v36
	s_waitcnt lgkmcnt(6)
	v_cvt_pk_bf16_f32 v32, v42, v40
	s_waitcnt lgkmcnt(4)
	v_cvt_pk_bf16_f32 v33, v44, v46
	s_waitcnt lgkmcnt(2)
	v_cvt_pk_bf16_f32 v34, v48, v50
	s_waitcnt lgkmcnt(0)
	v_cvt_pk_bf16_f32 v35, v54, v58
	v_lshl_add_u64 v[38:39], v[52:53], 0, v[38:39]
	v_lshlrev_b64 v[36:37], 11, v[36:37]
	global_store_dwordx4 v[38:39], v[32:35], off
	v_lshl_add_u64 v[36:37], v[52:53], 0, v[36:37]
	s_nop 0
	v_cvt_pk_bf16_f32 v32, v43, v41
	v_cvt_pk_bf16_f32 v33, v45, v47
	v_cvt_pk_bf16_f32 v34, v49, v51
	v_cvt_pk_bf16_f32 v35, v55, v59
	global_store_dwordx4 v[36:37], v[32:35], off
	s_waitcnt lgkmcnt(0)

.LBB0_21:
	s_andn2_b64 vcc, exec, s[4:5]
	s_cbranch_vccnz .LBB0_2
	s_mul_hi_i32 s2, s94, 0x2aaaaaab
	s_lshr_b32 s4, s2, 31
	s_ashr_i32 s2, s2, 4
	s_load_dwordx2 s[96:97], s[0:1], 0x48
	s_add_i32 s2, s2, s4
	s_lshl_b32 s4, s2, 6
	s_mulk_i32 s2, 0xf400
	s_add_i32 s5, s9, s93
	s_add_i32 s94, s5, s2
	s_ashr_i32 s95, s94, 31
	s_lshl_b64 s[94:95], s[94:95], 2
	s_waitcnt lgkmcnt(0)
	s_add_u32 s94, s96, s94
	v_or_b32_e32 v13, s4, v1
	s_addc_u32 s95, s97, s95
	v_lshl_add_u64 v[32:33], s[94:95], 0, v[2:3]
	v_or_b32_e32 v31, 2, v13
	v_mad_i64_i32 v[36:37], s[94:95], v31, s92, v[32:33]
	v_or_b32_e32 v31, 4, v13
	v_mad_i64_i32 v[38:39], s[94:95], v31, s92, v[32:33]
	v_or_b32_e32 v31, 6, v13
	v_mad_i64_i32 v[40:41], s[94:95], v31, s92, v[32:33]
	v_or_b32_e32 v31, 8, v13
	v_mad_i64_i32 v[42:43], s[94:95], v31, s92, v[32:33]
	v_or_b32_e32 v31, 10, v13
	v_mad_i64_i32 v[44:45], s[94:95], v31, s92, v[32:33]
	v_or_b32_e32 v31, 12, v13
	v_mad_i64_i32 v[46:47], s[94:95], v31, s92, v[32:33]
	v_or_b32_e32 v31, 14, v13
	v_mad_i64_i32 v[34:35], s[94:95], v13, s92, v[32:33]
	v_mad_i64_i32 v[48:49], s[94:95], v31, s92, v[32:33]
	global_load_dword v31, v[34:35], off nt
	global_load_dword v50, v[36:37], off nt
	global_load_dword v51, v[38:39], off nt
	global_load_dword v52, v[40:41], off nt
	global_load_dword v53, v[42:43], off nt
	global_load_dword v54, v[44:45], off nt
	global_load_dword v55, v[46:47], off nt
	global_load_dword v57, v[48:49], off nt
	v_or_b32_e32 v34, 16, v13
	v_or_b32_e32 v36, 18, v13
	v_or_b32_e32 v38, 20, v13
	v_or_b32_e32 v40, 22, v13
	v_or_b32_e32 v42, 24, v13
	v_or_b32_e32 v44, 26, v13
	v_or_b32_e32 v46, 28, v13
	v_or_b32_e32 v48, 30, v13
	v_mad_i64_i32 v[34:35], s[94:95], v34, s92, v[32:33]
	v_mad_i64_i32 v[36:37], s[94:95], v36, s92, v[32:33]
	v_mad_i64_i32 v[38:39], s[94:95], v38, s92, v[32:33]
	v_mad_i64_i32 v[40:41], s[94:95], v40, s92, v[32:33]
	v_mad_i64_i32 v[42:43], s[94:95], v42, s92, v[32:33]
	v_mad_i64_i32 v[44:45], s[94:95], v44, s92, v[32:33]
	v_mad_i64_i32 v[46:47], s[94:95], v46, s92, v[32:33]
	v_mad_i64_i32 v[48:49], s[94:95], v48, s92, v[32:33]
	global_load_dword v58, v[34:35], off nt
	global_load_dword v59, v[36:37], off nt
	global_load_dword v60, v[38:39], off nt
	global_load_dword v61, v[40:41], off nt
	global_load_dword v62, v[42:43], off nt
	global_load_dword v63, v[44:45], off nt
	global_load_dword v64, v[46:47], off nt
	global_load_dword v65, v[48:49], off nt
	v_or_b32_e32 v34, 32, v13
	v_or_b32_e32 v36, 34, v13
	v_or_b32_e32 v38, 36, v13
	v_or_b32_e32 v40, 38, v13
	v_or_b32_e32 v42, 40, v13
	v_or_b32_e32 v44, 42, v13
	v_or_b32_e32 v46, 44, v13
	v_or_b32_e32 v48, 46, v13
	v_mad_i64_i32 v[34:35], s[94:95], v34, s92, v[32:33]
	v_mad_i64_i32 v[36:37], s[94:95], v36, s92, v[32:33]
	v_mad_i64_i32 v[38:39], s[94:95], v38, s92, v[32:33]
	v_mad_i64_i32 v[40:41], s[94:95], v40, s92, v[32:33]
	v_mad_i64_i32 v[42:43], s[94:95], v42, s92, v[32:33]
	v_mad_i64_i32 v[44:45], s[94:95], v44, s92, v[32:33]
	v_mad_i64_i32 v[46:47], s[94:95], v46, s92, v[32:33]
	v_mad_i64_i32 v[48:49], s[94:95], v48, s92, v[32:33]
	global_load_dword v66, v[34:35], off nt
	global_load_dword v67, v[36:37], off nt
	global_load_dword v68, v[38:39], off nt
	global_load_dword v69, v[40:41], off nt
	global_load_dword v70, v[42:43], off nt
	global_load_dword v71, v[44:45], off nt
	global_load_dword v72, v[46:47], off nt
	s_nop 0
	global_load_dword v48, v[48:49], off nt
	v_or_b32_e32 v34, 48, v13
	v_or_b32_e32 v36, 50, v13
	v_or_b32_e32 v38, 52, v13
	v_or_b32_e32 v40, 54, v13
	v_or_b32_e32 v42, 56, v13
	v_or_b32_e32 v44, 58, v13
	v_or_b32_e32 v46, 60, v13
	v_or_b32_e32 v13, 62, v13
	v_mad_i64_i32 v[34:35], s[94:95], v34, s92, v[32:33]
	v_mad_i64_i32 v[36:37], s[94:95], v36, s92, v[32:33]
	v_mad_i64_i32 v[38:39], s[94:95], v38, s92, v[32:33]
	v_mad_i64_i32 v[40:41], s[94:95], v40, s92, v[32:33]
	v_mad_i64_i32 v[42:43], s[94:95], v42, s92, v[32:33]
	v_mad_i64_i32 v[44:45], s[94:95], v44, s92, v[32:33]
	v_mad_i64_i32 v[46:47], s[94:95], v46, s92, v[32:33]
	v_mad_i64_i32 v[32:33], s[94:95], v13, s92, v[32:33]
	global_load_dword v13, v[34:35], off nt
	s_nop 0
	global_load_dword v34, v[36:37], off nt
	global_load_dword v35, v[38:39], off nt
	s_nop 0
	global_load_dword v36, v[40:41], off nt
	global_load_dword v37, v[42:43], off nt
	global_load_dword v38, v[44:45], off nt
	global_load_dword v39, v[46:47], off nt
	s_nop 0
	global_load_dword v32, v[32:33], off nt
	s_waitcnt vmcnt(30)
	ds_write2_b32 v14, v31, v50 offset1:66
	s_waitcnt vmcnt(28)
	ds_write2_b32 v14, v51, v52 offset0:132 offset1:198
	s_waitcnt vmcnt(26)
	ds_write2_b32 v24, v53, v54 offset0:8 offset1:74
	s_waitcnt vmcnt(24)
	ds_write2_b32 v24, v55, v57 offset0:140 offset1:206
	s_waitcnt vmcnt(22)
	ds_write2_b32 v25, v58, v59 offset0:16 offset1:82
	s_waitcnt vmcnt(20)
	ds_write2_b32 v25, v60, v61 offset0:148 offset1:214
	s_waitcnt vmcnt(18)
	ds_write2_b32 v26, v62, v63 offset0:24 offset1:90
	s_waitcnt vmcnt(16)
	ds_write2_b32 v26, v64, v65 offset0:156 offset1:222
	s_waitcnt vmcnt(14)
	ds_write2_b32 v27, v66, v67 offset0:32 offset1:98
	s_waitcnt vmcnt(12)
	ds_write2_b32 v27, v68, v69 offset0:164 offset1:230
	s_waitcnt vmcnt(10)
	ds_write2_b32 v28, v70, v71 offset0:40 offset1:106
	s_waitcnt vmcnt(8)
	ds_write2_b32 v28, v72, v48 offset0:172 offset1:238
	s_waitcnt vmcnt(6)
	ds_write2_b32 v29, v13, v34 offset0:48 offset1:114
	s_waitcnt vmcnt(4)
	ds_write2_b32 v29, v35, v36 offset0:180 offset1:246
	s_waitcnt vmcnt(2)
	ds_write2_b32 v30, v37, v38 offset0:56 offset1:122
	s_waitcnt vmcnt(0)
	ds_write2_b32 v30, v39, v32 offset0:188 offset1:254
	s_waitcnt lgkmcnt(0)
	ds_read2_b32 v[36:37], v16 offset0:33 offset1:41
	ds_read2_b32 v[38:39], v16 offset1:8
	ds_read2_b32 v[40:41], v16 offset0:66 offset1:74
	ds_read2_b32 v[42:43], v16 offset0:99 offset1:107
	ds_read2_b32 v[44:45], v16 offset0:132 offset1:140
	ds_read2_b32 v[46:47], v16 offset0:165 offset1:173
	ds_read2_b32 v[48:49], v16 offset0:198 offset1:206
	ds_read2_b32 v[50:51], v16 offset0:231 offset1:239
	s_add_i32 s2, s2, s93
	v_add_u32_e32 v54, s2, v23
	s_ashr_i32 s5, s4, 31
	v_ashrrev_i32_e32 v55, 31, v54
	v_lshl_add_u64 v[52:53], s[4:5], 1, v[10:11]
	v_lshlrev_b64 v[58:59], 11, v[54:55]
	s_waitcnt lgkmcnt(6)
	v_cvt_pk_bf16_f32 v32, v38, v36
	s_waitcnt lgkmcnt(4)
	v_cvt_pk_bf16_f32 v33, v40, v42
	s_waitcnt lgkmcnt(2)
	v_cvt_pk_bf16_f32 v34, v44, v46
	s_waitcnt lgkmcnt(0)
	v_cvt_pk_bf16_f32 v35, v48, v50
	v_lshl_add_u64 v[58:59], v[52:53], 0, v[58:59]
	v_add_u32_e32 v36, 8, v54
	global_store_dwordx4 v[58:59], v[32:35], off
	s_nop 1
	v_cvt_pk_bf16_f32 v32, v39, v37
	v_ashrrev_i32_e32 v37, 31, v36
	v_cvt_pk_bf16_f32 v33, v41, v43
	v_cvt_pk_bf16_f32 v34, v45, v47
	v_cvt_pk_bf16_f32 v35, v49, v51
	v_lshlrev_b64 v[36:37], 11, v[36:37]
	ds_read2_b32 v[38:39], v16 offset0:49 offset1:57
	ds_read2_b32 v[40:41], v16 offset0:16 offset1:24
	ds_read2_b32 v[42:43], v16 offset0:82 offset1:90
	ds_read2_b32 v[44:45], v16 offset0:115 offset1:123
	ds_read2_b32 v[46:47], v16 offset0:148 offset1:156
	ds_read2_b32 v[48:49], v16 offset0:181 offset1:189
	ds_read2_b32 v[50:51], v16 offset0:214 offset1:222
	ds_read2_b32 v[58:59], v16 offset0:247 offset1:255
	v_lshl_add_u64 v[36:37], v[52:53], 0, v[36:37]
	global_store_dwordx4 v[36:37], v[32:35], off
	v_add_u32_e32 v36, 16, v54
	v_ashrrev_i32_e32 v37, 31, v36
	v_lshlrev_b64 v[36:37], 11, v[36:37]
	s_waitcnt lgkmcnt(6)
	v_cvt_pk_bf16_f32 v32, v40, v38
	s_waitcnt lgkmcnt(4)
	v_cvt_pk_bf16_f32 v33, v42, v44
	s_waitcnt lgkmcnt(2)
	v_cvt_pk_bf16_f32 v34, v46, v48
	s_waitcnt lgkmcnt(0)
	v_cvt_pk_bf16_f32 v35, v50, v58
	v_lshl_add_u64 v[36:37], v[52:53], 0, v[36:37]
	global_store_dwordx4 v[36:37], v[32:35], off
	v_add_u32_e32 v36, 24, v54
	v_ashrrev_i32_e32 v37, 31, v36
	v_lshlrev_b64 v[36:37], 11, v[36:37]
	v_cvt_pk_bf16_f32 v32, v41, v39
	v_cvt_pk_bf16_f32 v33, v43, v45
	v_cvt_pk_bf16_f32 v34, v47, v49
	v_cvt_pk_bf16_f32 v35, v51, v59
	v_lshl_add_u64 v[36:37], v[52:53], 0, v[36:37]
	global_store_dwordx4 v[36:37], v[32:35], off
	s_waitcnt lgkmcnt(0)
	s_branch .LBB0_2

.LBB0_27:
	v_ashrrev_i32_e32 v13, 3, v2
	v_mad_i64_i32 v[14:15], s[14:15], v13, s12, v[4:5]
	v_ashrrev_i32_e32 v1, 3, v3
	v_lshl_add_u64 v[14:15], v[14:15], 0, v[6:7]
	v_add_u32_e32 v18, 0x400, v2
	v_mad_i64_i32 v[16:17], s[14:15], v1, s12, v[4:5]
	v_add_co_u32_e32 v14, vcc, 0x3000, v14
	v_add_u32_e32 v19, 0x400, v3
	v_ashrrev_i32_e32 v23, 3, v18
	v_lshl_add_u64 v[16:17], v[16:17], 0, v[6:7]
	v_addc_co_u32_e32 v15, vcc, 0, v15, vcc
	v_ashrrev_i32_e32 v22, 3, v19
	v_mad_i64_i32 v[18:19], s[14:15], v23, s12, v[4:5]
	v_add_co_u32_e32 v16, vcc, 0x3000, v16
	v_lshl_add_u64 v[18:19], v[18:19], 0, v[6:7]
	s_nop 0
	v_addc_co_u32_e32 v17, vcc, 0, v17, vcc
	v_mad_i64_i32 v[20:21], s[14:15], v22, s12, v[4:5]
	v_add_co_u32_e32 v18, vcc, s13, v18
	v_lshl_add_u64 v[20:21], v[20:21], 0, v[6:7]
	s_nop 0
	v_addc_co_u32_e32 v19, vcc, 0, v19, vcc
	global_load_dword v24, v[14:15], off nt
	global_load_dword v25, v[16:17], off nt
	v_add_co_u32_e32 v14, vcc, s13, v20
	v_add_u32_e32 v12, -2, v12
	s_nop 0
	v_addc_co_u32_e32 v15, vcc, 0, v21, vcc
	global_load_dword v16, v[18:19], off nt
	global_load_dword v17, v[14:15], off nt
	v_cmp_eq_u32_e32 vcc, 0, v12
	v_add_u32_e32 v3, 0x800, v3
	v_add_u32_e32 v2, 0x800, v2
	v_lshl_add_u32 v13, v13, 2, v8
	s_or_b64 s[10:11], vcc, s[10:11]
	v_lshl_add_u32 v1, v1, 2, v8
	v_lshl_add_u32 v14, v23, 2, v8
	v_lshl_add_u32 v15, v22, 2, v8
	s_waitcnt vmcnt(3)
	ds_write_b32 v13, v24
	s_waitcnt vmcnt(2)
	ds_write_b32 v1, v25
	s_waitcnt vmcnt(1)
	ds_write_b32 v14, v16
	s_waitcnt vmcnt(0)
	ds_write_b32 v15, v17
	s_andn2_b64 exec, exec, s[10:11]
	s_cbranch_execnz .LBB0_27
	s_or_b64 exec, exec, s[10:11]
.LBB0_29:
	s_or_b64 exec, exec, s[8:9]
	v_and_b32_e32 v1, 2, v11
	v_cmp_eq_u32_e32 vcc, 0, v1
	s_and_saveexec_b64 s[8:9], vcc
	s_cbranch_execz .LBB0_31
	v_ashrrev_i32_e32 v1, 3, v3
	v_ashrrev_i32_e32 v11, 3, v2
	s_movk_i32 s12, 0x3020
	s_waitcnt lgkmcnt(0)
	v_mov_b64_e32 v[2:3], s[4:5]
	v_mad_i64_i32 v[4:5], s[10:11], v11, s12, v[2:3]
	v_lshlrev_b32_e32 v6, 2, v9
	v_mov_b32_e32 v7, 0
	v_lshl_add_u64 v[4:5], v[4:5], 0, v[6:7]
	v_mad_i64_i32 v[2:3], s[10:11], v1, s12, v[2:3]
	v_add_co_u32_e32 v4, vcc, 0x3000, v4
	v_lshl_add_u64 v[2:3], v[2:3], 0, v[6:7]
	s_nop 0
	v_addc_co_u32_e32 v5, vcc, 0, v5, vcc
	v_add_co_u32_e32 v2, vcc, 0x3000, v2
	v_lshl_add_u32 v1, v1, 2, v8
	s_nop 0
	v_addc_co_u32_e32 v3, vcc, 0, v3, vcc
	global_load_dword v6, v[4:5], off nt
	global_load_dword v7, v[2:3], off nt
	v_lshl_add_u32 v2, v11, 2, v8
	s_waitcnt vmcnt(1)
	ds_write_b32 v2, v6
	s_waitcnt vmcnt(0)
	ds_write_b32 v1, v7

.LBB0_34:
	v_ashrrev_i32_e32 v1, 3, v0
	v_mad_i64_i32 v[6:7], s[10:11], v1, s8, v[2:3]
	v_lshl_add_u64 v[6:7], v[6:7], 0, v[4:5]
	v_add_co_u32_e32 v6, vcc, 0x3000, v6
	v_lshl_add_u32 v1, v1, 2, v8
	s_nop 0
	v_addc_co_u32_e32 v7, vcc, 0, v7, vcc
	global_load_dword v6, v[6:7], off nt
	v_add_u32_e32 v7, 0x200, v0
	v_cmp_lt_i32_e32 vcc, s4, v0
	s_or_b64 s[6:7], vcc, s[6:7]
	v_mov_b32_e32 v0, v7
	s_waitcnt vmcnt(0)
	ds_write_b32 v1, v6
	s_andn2_b64 exec, exec, s[6:7]
	s_cbranch_execnz .LBB0_34
.LBB0_35:
	s_or_b64 exec, exec, s[2:3]
	s_cmpk_lt_i32 s20, 0x4200
	s_waitcnt lgkmcnt(0)
	s_barrier
	s_cbranch_scc0 .LBB0_44
	s_load_dwordx2 s[2:3], s[0:1], 0xa0
	v_lshlrev_b32_e32 v16, 4, v144
	v_mbcnt_lo_u32_b32 v17, -1, 0
	v_mbcnt_hi_u32_b32 v17, -1, v17
	v_and_b32_e32 v18, 64, v17
	s_waitcnt lgkmcnt(0)
	global_load_dwordx4 v[0:3], v16, s[2:3] nt
	global_load_dwordx4 v[4:7], v16, s[2:3] offset:1024 nt
	global_load_dwordx4 v[8:11], v16, s[2:3] offset:2048 nt
	global_load_dwordx4 v[12:15], v16, s[2:3] offset:3072 nt
	v_add_u32_e32 v18, 64, v18
	v_xor_b32_e32 v19, 1, v17
	v_cmp_lt_i32_e32 vcc, v19, v18
	v_mov_b32_e32 v57, 0
	v_add_u32_e32 v16, 0, v16
	v_cndmask_b32_e32 v19, v17, v19, vcc
	v_lshlrev_b32_e32 v145, 2, v19
	v_xor_b32_e32 v19, 2, v17
	v_cmp_lt_i32_e32 vcc, v19, v18
	v_lshl_add_u64 v[56:57], s[24:25], 0, v[56:57]
	s_mov_b64 s[24:25], 0x3100000
	v_cndmask_b32_e32 v19, v17, v19, vcc
	v_lshlrev_b32_e32 v174, 2, v19
	v_xor_b32_e32 v19, 4, v17
	v_cmp_lt_i32_e32 vcc, v19, v18
	v_add_u32_e32 v140, 0x18000, v16
	v_lshl_add_u64 v[146:147], v[56:57], 0, s[24:25]
	v_cndmask_b32_e32 v19, v17, v19, vcc
	v_lshlrev_b32_e32 v175, 2, v19
	v_xor_b32_e32 v19, 8, v17
	v_cmp_lt_i32_e32 vcc, v19, v18
	s_ashr_i32 s21, s20, 31
	s_ashr_i32 s23, s22, 31
	v_cndmask_b32_e32 v19, v17, v19, vcc
	v_lshlrev_b32_e32 v176, 2, v19
	v_xor_b32_e32 v19, 16, v17
	v_cmp_lt_i32_e32 vcc, v19, v18
	s_mov_b32 s27, 0
	v_cmp_gt_u32_e64 s[2:3], 8, v144
	v_cndmask_b32_e32 v19, v17, v19, vcc
	v_lshlrev_b32_e32 v177, 2, v19
	v_xor_b32_e32 v19, 32, v17
	v_cmp_lt_i32_e32 vcc, v19, v18
	v_cmp_eq_u32_e64 s[4:5], 7, v144
	v_cmp_eq_u32_e64 s[6:7], 6, v144
	v_cndmask_b32_e32 v17, v17, v19, vcc
	v_lshlrev_b32_e32 v178, 2, v17
	ds_read_b128 v[16:19], v140
	ds_read_b128 v[20:23], v140 offset:1024
	ds_read_b128 v[24:27], v140 offset:2048
	ds_read_b128 v[28:31], v140 offset:3072
	ds_read_b128 v[32:35], v140 offset:4096
	ds_read_b128 v[36:39], v140 offset:5120
	ds_read_b128 v[40:43], v140 offset:6144
	ds_read_b128 v[44:47], v140 offset:7168
	ds_read_b128 v[48:51], v140 offset:8192
	ds_read_b128 v[52:55], v140 offset:9216
	ds_read_b128 v[56:59], v140 offset:10240
	ds_read_b128 v[60:63], v140 offset:11264
	ds_read_b128 v[64:67], v140 offset:12288
	ds_read_b128 v[68:71], v140 offset:13312
	ds_read_b128 v[72:75], v140 offset:14336
	ds_read_b128 v[76:79], v140 offset:15360
	ds_read_b128 v[80:83], v140 offset:16384
	ds_read_b128 v[84:87], v140 offset:17408
	ds_read_b128 v[88:91], v140 offset:18432
	ds_read_b128 v[92:95], v140 offset:19456
	ds_read_b128 v[96:99], v140 offset:20480
	ds_read_b128 v[100:103], v140 offset:21504
	ds_read_b128 v[104:107], v140 offset:22528
	ds_read_b128 v[108:111], v140 offset:23552
	ds_read_b128 v[112:115], v140 offset:24576
	ds_read_b128 v[116:119], v140 offset:25600
	ds_read_b128 v[120:123], v140 offset:26624
	ds_read_b128 v[124:127], v140 offset:27648
	ds_read_b128 v[128:131], v140 offset:28672
	ds_read_b128 v[132:135], v140 offset:29696
	ds_read_b128 v[136:139], v140 offset:30720
	ds_read_b128 v[140:143], v140 offset:31744
	v_cmp_eq_u32_e64 s[8:9], 5, v144
	v_cmp_eq_u32_e64 s[10:11], 4, v144
	v_cmp_eq_u32_e64 s[12:13], 3, v144
	v_cmp_eq_u32_e64 s[14:15], 2, v144
	v_cmp_eq_u32_e64 s[16:17], 1, v144
	v_cmp_eq_u32_e64 s[18:19], 0, v144
	s_lshl_b64 s[24:25], s[20:21], 12
	s_lshl_b64 s[28:29], s[22:23], 12
	v_mov_b32_e32 v179, 0x358637bd
	s_mov_b32 s33, 0x800000
	s_mov_b32 s40, 0xbfb8aa3b
	s_mov_b32 s41, 0xb2a5705f
	s_mov_b32 s42, 0x42ce8ed0
	s_mov_b32 s43, 0xc2b17218
	s_mov_b32 s44, 0x7f800000
	s_mov_b32 s45, 0x3f2aaaab
	v_mov_b32_e32 v180, 0x3ecc95a3
	s_mov_b32 s46, 0x3f317218
	s_mov_b32 s47, 0x33800000
	s_mov_b32 s48, 0xc200000
	v_mov_b32_e32 v181, 0x7f800000
	v_mov_b32_e32 v148, 0x3f317218
	s_branch .LBB0_38

.LBB0_42:
	v_lshlrev_b32_e32 v149, 4, v144
	global_load_dwordx4 v[152:155], v149, s[36:37] nt
	global_load_dwordx4 v[156:159], v149, s[36:37] offset:1024 nt
	s_waitcnt lgkmcnt(6)
	global_load_dwordx4 v[160:163], v149, s[36:37] offset:2048 nt
	s_waitcnt lgkmcnt(4)
	global_load_dwordx4 v[164:167], v149, s[36:37] offset:3072 nt
	s_lshl_b64 s[36:37], s[34:35], 11
	s_waitcnt vmcnt(3)
	v_pk_mul_f32 v[150:151], v[154:155], v[154:155]
	s_waitcnt lgkmcnt(3)
	v_pk_mul_f32 v[168:169], v[152:153], v[152:153]
	s_waitcnt vmcnt(2) lgkmcnt(1)
	v_pk_mul_f32 v[170:171], v[158:159], v[158:159]
	s_waitcnt lgkmcnt(0)
	v_pk_mul_f32 v[172:173], v[156:157], v[156:157]
	v_pk_mov_b32 v[186:187], v[168:169], v[150:151] op_sel:[1,0]
	v_mov_b32_e32 v169, v151
	v_pk_mov_b32 v[150:151], v[172:173], v[170:171] op_sel:[1,0]
	v_mov_b32_e32 v173, v171
	s_waitcnt vmcnt(1)
	v_mul_f32_e32 v182, v161, v161
	v_mul_f32_e32 v184, v163, v163
	s_waitcnt vmcnt(0)
	v_mul_f32_e32 v185, v167, v167
	v_pk_add_f32 v[168:169], v[186:187], v[168:169]
	v_pk_add_f32 v[150:151], v[150:151], v[172:173]
	v_mul_f32_e32 v149, v166, v166
	v_mul_f32_e32 v188, v164, v164
	v_mul_f32_e32 v189, v165, v165
	v_pk_fma_f32 v[170:171], v[160:161], v[160:161], v[182:183] op_sel_hi:[1,1,0]
	v_pk_fma_f32 v[182:183], v[162:163], v[162:163], v[184:185] op_sel_hi:[1,1,0]
	v_pk_add_f32 v[168:169], v[168:169], v[168:169] op_sel:[0,1] op_sel_hi:[1,0]
	v_pk_add_f32 v[150:151], v[150:151], v[150:151] op_sel:[0,1] op_sel_hi:[1,0]
	v_mov_b32_e32 v171, v149
	v_mov_b32_e32 v183, v185
	v_mov_b32_e32 v169, v188
	v_mov_b32_e32 v151, v189
	v_pk_add_f32 v[170:171], v[170:171], v[182:183]
	v_pk_add_f32 v[150:151], v[168:169], v[150:151]
	s_nop 0
	v_pk_add_f32 v[150:151], v[150:151], v[170:171]
	s_nop 0
	v_add_f32_e32 v149, v150, v151
	ds_bpermute_b32 v150, v145, v149
	s_waitcnt lgkmcnt(0)
	v_add_f32_e32 v149, v149, v150
	ds_bpermute_b32 v150, v174, v149
	s_waitcnt lgkmcnt(0)
	v_add_f32_e32 v149, v149, v150
	ds_bpermute_b32 v150, v175, v149
	s_waitcnt lgkmcnt(0)
	v_add_f32_e32 v149, v149, v150
	ds_bpermute_b32 v150, v176, v149
	s_waitcnt lgkmcnt(0)
	v_add_f32_e32 v149, v149, v150
	ds_bpermute_b32 v150, v177, v149
	s_waitcnt lgkmcnt(0)
	v_add_f32_e32 v149, v149, v150
	ds_bpermute_b32 v150, v178, v149
	s_waitcnt lgkmcnt(0)
	v_add_f32_e32 v149, v149, v150
	v_fmamk_f32 v149, v149, 0x3a800000, v179
	v_mul_f32_e32 v150, 0x4b800000, v149
	v_cmp_gt_f32_e32 vcc, s33, v149
	s_nop 1
	v_cndmask_b32_e32 v149, v149, v150, vcc
	v_rsq_f32_e32 v149, v149
	v_lshl_add_u64 v[150:151], v[146:147], 0, s[36:37]
	v_mul_f32_e32 v168, 0x45800000, v149
	v_cndmask_b32_e32 v168, v149, v168, vcc
	v_pk_mul_f32 v[156:157], v[156:157], v[168:169] op_sel_hi:[1,0]
	v_pk_mul_f32 v[152:153], v[152:153], v[168:169] op_sel_hi:[1,0]
	v_pk_mul_f32 v[154:155], v[154:155], v[168:169] op_sel_hi:[1,0]
	v_pk_mul_f32 v[158:159], v[158:159], v[168:169] op_sel_hi:[1,0]
	v_pk_mul_f32 v[172:173], v[164:165], v[168:169] op_sel_hi:[1,0]
	v_pk_mul_f32 v[164:165], v[4:5], v[156:157]
	v_pk_mul_f32 v[160:161], v[160:161], v[168:169] op_sel_hi:[1,0]
	v_pk_mul_f32 v[170:171], v[162:163], v[168:169] op_sel_hi:[1,0]
	v_pk_mul_f32 v[182:183], v[166:167], v[168:169] op_sel_hi:[1,0]
	v_pk_mul_f32 v[166:167], v[2:3], v[154:155]
	v_pk_mul_f32 v[168:169], v[0:1], v[152:153]
	v_pk_mul_f32 v[162:163], v[6:7], v[158:159]
	v_pk_mul_f32 v[154:155], v[12:13], v[172:173]
	v_cvt_pk_bf16_f32 v172, v164, v165
	v_mul_f32_e32 v195, v21, v165
	v_mul_f32_e32 v196, v37, v165
	v_mul_f32_e32 v197, v53, v165
	v_mul_f32_e32 v198, v69, v165
	v_mul_f32_e32 v199, v85, v165
	v_mul_f32_e32 v200, v101, v165
	v_mul_f32_e32 v201, v117, v165
	v_mul_f32_e32 v165, v133, v165
	v_pk_mul_f32 v[158:159], v[10:11], v[170:171]
	v_pk_mul_f32 v[160:161], v[8:9], v[160:161]
	v_pk_mul_f32 v[152:153], v[14:15], v[182:183]
	v_cvt_pk_bf16_f32 v170, v168, v169
	v_cvt_pk_bf16_f32 v171, v166, v167
	v_cvt_pk_bf16_f32 v173, v162, v163
	v_mul_f32_e32 v149, v17, v169
	v_mul_f32_e32 v182, v33, v169
	v_mul_f32_e32 v183, v49, v169
	v_mul_f32_e32 v184, v65, v169
	v_mul_f32_e32 v185, v81, v169
	v_mul_f32_e32 v186, v97, v169
	v_mul_f32_e32 v187, v113, v169
	v_mul_f32_e32 v169, v129, v169
	v_mul_f32_e32 v188, v19, v167
	v_mul_f32_e32 v189, v35, v167
	v_mul_f32_e32 v190, v51, v167
	v_mul_f32_e32 v191, v67, v167
	v_mul_f32_e32 v192, v83, v167
	v_mul_f32_e32 v193, v99, v167
	v_mul_f32_e32 v194, v115, v167
	v_mul_f32_e32 v167, v131, v167
	v_mul_f32_e32 v202, v23, v163
	v_mul_f32_e32 v203, v39, v163
	v_mul_f32_e32 v204, v55, v163
	v_mul_f32_e32 v205, v71, v163
	v_mul_f32_e32 v206, v87, v163
	v_mul_f32_e32 v207, v103, v163
	v_fmac_f32_e32 v195, v20, v164
	v_fmac_f32_e32 v196, v36, v164
	v_fmac_f32_e32 v197, v52, v164
	v_fmac_f32_e32 v198, v68, v164
	v_fmac_f32_e32 v199, v84, v164
	v_fmac_f32_e32 v200, v100, v164
	v_fmac_f32_e32 v201, v116, v164
	v_fmac_f32_e32 v165, v132, v164
	v_mul_f32_e32 v164, v119, v163
	v_mul_f32_e32 v163, v135, v163
	v_cvt_pk_bf16_f32 v156, v160, v161
	global_store_dwordx2 v[150:151], v[170:171], off
	global_store_dwordx2 v[150:151], v[172:173], off offset:512
	v_fmac_f32_e32 v149, v16, v168
	v_fmac_f32_e32 v182, v32, v168
	v_fmac_f32_e32 v183, v48, v168
	v_fmac_f32_e32 v184, v64, v168
	v_fmac_f32_e32 v185, v80, v168
	v_fmac_f32_e32 v186, v96, v168
	v_fmac_f32_e32 v187, v112, v168
	v_fmac_f32_e32 v169, v128, v168
	v_fmac_f32_e32 v188, v18, v166
	v_fmac_f32_e32 v189, v34, v166
	v_fmac_f32_e32 v190, v50, v166
	v_fmac_f32_e32 v191, v66, v166
	v_fmac_f32_e32 v192, v82, v166
	v_fmac_f32_e32 v193, v98, v166
	v_fmac_f32_e32 v194, v114, v166
	v_fmac_f32_e32 v167, v130, v166
	v_fmac_f32_e32 v202, v22, v162
	v_fmac_f32_e32 v203, v38, v162
	v_fmac_f32_e32 v204, v54, v162
	v_fmac_f32_e32 v205, v70, v162
	v_fmac_f32_e32 v206, v86, v162
	v_fmac_f32_e32 v207, v102, v162
	v_fmac_f32_e32 v164, v118, v162
	v_fmac_f32_e32 v163, v134, v162
	v_mul_f32_e32 v162, v25, v161
	v_mul_f32_e32 v166, v41, v161
	v_mul_f32_e32 v168, v57, v161
	v_mul_f32_e32 v170, v73, v161
	v_mul_f32_e32 v171, v89, v161
	v_mul_f32_e32 v172, v105, v161
	v_mul_f32_e32 v173, v121, v161
	v_mul_f32_e32 v161, v137, v161
	v_fmac_f32_e32 v162, v24, v160
	v_fmac_f32_e32 v166, v40, v160
	v_fmac_f32_e32 v168, v56, v160
	v_fmac_f32_e32 v170, v72, v160
	v_fmac_f32_e32 v171, v88, v160
	v_fmac_f32_e32 v172, v104, v160
	v_fmac_f32_e32 v173, v120, v160
	v_fmac_f32_e32 v161, v136, v160
	v_mul_f32_e32 v160, v27, v159
	v_mul_f32_e32 v208, v43, v159
	v_mul_f32_e32 v209, v59, v159
	v_mul_f32_e32 v210, v75, v159
	v_mul_f32_e32 v211, v91, v159
	v_mul_f32_e32 v212, v107, v159
	v_mul_f32_e32 v213, v123, v159
	v_mul_f32_e32 v214, v139, v159
	v_add_f32_e32 v149, v149, v188
	v_cvt_pk_bf16_f32 v157, v158, v159
	v_fmac_f32_e32 v160, v26, v158
	v_fmac_f32_e32 v208, v42, v158
	v_fmac_f32_e32 v209, v58, v158
	v_fmac_f32_e32 v210, v74, v158
	v_fmac_f32_e32 v211, v90, v158
	v_fmac_f32_e32 v212, v106, v158
	v_fmac_f32_e32 v213, v122, v158
	v_fmac_f32_e32 v214, v138, v158
	v_mul_f32_e32 v158, v29, v155
	v_mul_f32_e32 v221, v31, v153
	v_add_f32_e32 v188, v195, v202
	v_add_f32_e32 v149, 0, v149
	v_fmac_f32_e32 v158, v28, v154
	v_fmac_f32_e32 v221, v30, v152
	v_add_f32_e32 v149, v188, v149
	v_add_f32_e32 v160, v162, v160
	v_add_f32_e32 v149, v160, v149
	v_add_f32_e32 v158, v158, v221
	v_add_f32_e32 v149, v158, v149
	ds_bpermute_b32 v158, v145, v149
	v_add_f32_e32 v182, v182, v189
	v_mul_f32_e32 v159, v45, v155
	v_mul_f32_e32 v222, v47, v153
	v_add_f32_e32 v188, v196, v203
	v_add_f32_e32 v182, 0, v182
	v_fmac_f32_e32 v159, v44, v154
	v_fmac_f32_e32 v222, v46, v152
	v_add_f32_e32 v182, v188, v182
	v_add_f32_e32 v166, v166, v208
	v_add_f32_e32 v166, v166, v182
	v_add_f32_e32 v159, v159, v222
	s_waitcnt lgkmcnt(0)
	v_add_f32_e32 v149, v149, v158
	v_add_f32_e32 v159, v159, v166
	ds_bpermute_b32 v158, v174, v149
	ds_bpermute_b32 v166, v145, v159
	v_add_f32_e32 v183, v183, v190
	v_mul_f32_e32 v215, v61, v155
	v_mul_f32_e32 v223, v63, v153
	s_waitcnt lgkmcnt(1)
	v_add_f32_e32 v149, v149, v158
	s_waitcnt lgkmcnt(0)
	v_add_f32_e32 v159, v159, v166
	ds_bpermute_b32 v158, v175, v149
	ds_bpermute_b32 v166, v174, v159
	v_add_f32_e32 v190, v197, v204
	v_add_f32_e32 v183, 0, v183
	v_fmac_f32_e32 v215, v60, v154
	s_waitcnt lgkmcnt(1)
	v_add_f32_e32 v149, v149, v158
	s_waitcnt lgkmcnt(0)
	v_add_f32_e32 v159, v159, v166
	ds_bpermute_b32 v158, v176, v149
	ds_bpermute_b32 v166, v175, v159
	v_fmac_f32_e32 v223, v62, v152
	v_add_f32_e32 v183, v190, v183
	v_add_f32_e32 v168, v168, v209
	v_add_f32_e32 v168, v168, v183
	v_add_f32_e32 v183, v215, v223
	s_waitcnt lgkmcnt(1)
	v_add_f32_e32 v149, v149, v158
	s_waitcnt lgkmcnt(0)
	v_add_f32_e32 v159, v159, v166
	v_add_f32_e32 v168, v183, v168
	ds_bpermute_b32 v158, v177, v149
	ds_bpermute_b32 v166, v176, v159
	ds_bpermute_b32 v183, v145, v168
	v_add_f32_e32 v170, v170, v210
	v_mul_f32_e32 v216, v77, v155
	s_waitcnt lgkmcnt(2)
	v_add_f32_e32 v149, v149, v158
	s_waitcnt lgkmcnt(1)
	v_add_f32_e32 v158, v159, v166
	s_waitcnt lgkmcnt(0)
	v_add_f32_e32 v166, v168, v183
	v_add_f32_e32 v183, v184, v191
	v_add_f32_e32 v184, v198, v205
	v_add_f32_e32 v183, 0, v183
	v_add_f32_e32 v183, v184, v183
	v_mul_f32_e32 v160, v79, v153
	v_add_f32_e32 v170, v170, v183
	v_add_f32_e32 v183, v185, v192
	v_fmac_f32_e32 v216, v76, v154
	v_mul_f32_e32 v217, v93, v155
	v_fmac_f32_e32 v160, v78, v152
	v_mul_f32_e32 v162, v95, v153
	v_add_f32_e32 v184, v199, v206
	v_add_f32_e32 v183, 0, v183
	v_fmac_f32_e32 v217, v92, v154
	v_fmac_f32_e32 v162, v94, v152
	v_add_f32_e32 v160, v216, v160
	v_add_f32_e32 v183, v184, v183
	v_add_f32_e32 v171, v171, v211
	v_add_f32_e32 v160, v160, v170
	v_add_f32_e32 v171, v171, v183
	v_add_f32_e32 v162, v217, v162
	ds_bpermute_b32 v170, v145, v160
	v_add_f32_e32 v162, v162, v171
	ds_bpermute_b32 v171, v145, v162
	v_add_f32_e32 v167, v169, v167
	v_mul_f32_e32 v218, v109, v155
	s_waitcnt lgkmcnt(1)
	v_add_f32_e32 v160, v160, v170
	ds_bpermute_b32 v170, v174, v160
	s_waitcnt lgkmcnt(1)
	v_add_f32_e32 v162, v162, v171
	ds_bpermute_b32 v171, v174, v162
	v_mul_f32_e32 v219, v125, v155
	v_mul_f32_e32 v220, v141, v155
	s_waitcnt lgkmcnt(1)
	v_add_f32_e32 v160, v160, v170
	ds_bpermute_b32 v170, v175, v160
	s_waitcnt lgkmcnt(1)
	v_add_f32_e32 v162, v162, v171
	ds_bpermute_b32 v171, v175, v162
	v_mul_f32_e32 v182, v111, v153
	v_mul_f32_e32 v188, v127, v153
	s_waitcnt lgkmcnt(1)
	v_add_f32_e32 v160, v160, v170
	ds_bpermute_b32 v170, v176, v160
	s_waitcnt lgkmcnt(1)
	v_add_f32_e32 v162, v162, v171
	ds_bpermute_b32 v171, v176, v162
	v_mul_f32_e32 v189, v143, v153
	v_add_f32_e32 v164, v201, v164
	s_waitcnt lgkmcnt(1)
	v_add_f32_e32 v160, v160, v170
	v_add_f32_e32 v170, v186, v193
	s_waitcnt lgkmcnt(0)
	v_add_f32_e32 v162, v162, v171
	v_add_f32_e32 v171, v200, v207
	v_add_f32_e32 v170, 0, v170
	v_add_f32_e32 v170, v171, v170
	v_add_f32_e32 v171, v172, v212
	v_add_f32_e32 v172, v187, v194
	v_add_f32_e32 v172, 0, v172
	v_add_f32_e32 v163, v165, v163
	v_add_f32_e32 v165, 0, v167
	v_fmac_f32_e32 v218, v108, v154
	v_fmac_f32_e32 v219, v124, v154
	v_fmac_f32_e32 v220, v140, v154
	v_fmac_f32_e32 v182, v110, v152
	v_fmac_f32_e32 v188, v126, v152
	v_fmac_f32_e32 v189, v142, v152
	v_add_f32_e32 v164, v164, v172
	v_add_f32_e32 v172, v173, v213
	v_add_f32_e32 v163, v163, v165
	v_add_f32_e32 v161, v161, v214
	v_add_f32_e32 v170, v171, v170
	v_add_f32_e32 v171, v218, v182
	v_add_f32_e32 v164, v172, v164
	v_add_f32_e32 v172, v219, v188
	v_add_f32_e32 v161, v161, v163
	v_add_f32_e32 v163, v220, v189
	v_add_f32_e32 v170, v171, v170
	v_add_f32_e32 v164, v172, v164
	v_add_f32_e32 v161, v163, v161
	ds_bpermute_b32 v171, v145, v170
	ds_bpermute_b32 v172, v145, v164
	ds_bpermute_b32 v163, v145, v161
	ds_bpermute_b32 v168, v174, v166
	ds_bpermute_b32 v159, v177, v158
	s_waitcnt lgkmcnt(4)
	v_add_f32_e32 v165, v170, v171
	s_waitcnt lgkmcnt(3)
	v_add_f32_e32 v164, v164, v172
	s_waitcnt lgkmcnt(2)
	v_add_f32_e32 v161, v161, v163
	s_waitcnt lgkmcnt(1)
	v_add_f32_e32 v166, v166, v168
	ds_bpermute_b32 v167, v174, v165
	ds_bpermute_b32 v169, v174, v164
	ds_bpermute_b32 v163, v174, v161
	ds_bpermute_b32 v168, v175, v166
	s_waitcnt lgkmcnt(4)
	v_add_f32_e32 v158, v158, v159
	s_waitcnt lgkmcnt(3)
	v_add_f32_e32 v165, v165, v167
	s_waitcnt lgkmcnt(2)
	v_add_f32_e32 v164, v164, v169
	s_waitcnt lgkmcnt(1)
	v_add_f32_e32 v161, v161, v163
	s_waitcnt lgkmcnt(0)
	v_add_f32_e32 v166, v166, v168
	ds_bpermute_b32 v167, v175, v165
	ds_bpermute_b32 v169, v175, v164
	ds_bpermute_b32 v163, v175, v161
	ds_bpermute_b32 v168, v176, v166
	v_cvt_pk_bf16_f32 v154, v154, v155
	s_waitcnt lgkmcnt(3)
	v_add_f32_e32 v165, v165, v167
	s_waitcnt lgkmcnt(2)
	v_add_f32_e32 v164, v164, v169
	s_waitcnt lgkmcnt(1)
	v_add_f32_e32 v161, v161, v163
	s_waitcnt lgkmcnt(0)
	v_add_f32_e32 v166, v166, v168
	ds_bpermute_b32 v167, v176, v165
	ds_bpermute_b32 v169, v176, v164
	ds_bpermute_b32 v163, v176, v161
	ds_bpermute_b32 v168, v177, v166
	v_cvt_pk_bf16_f32 v155, v152, v153
	s_waitcnt lgkmcnt(3)
	v_add_f32_e32 v165, v165, v167
	s_waitcnt lgkmcnt(2)
	v_add_f32_e32 v169, v164, v169
	s_waitcnt lgkmcnt(1)
	v_add_f32_e32 v161, v161, v163
	s_waitcnt lgkmcnt(0)
	v_add_f32_e32 v159, v166, v168
	ds_bpermute_b32 v166, v177, v160
	ds_bpermute_b32 v168, v177, v162
	ds_bpermute_b32 v167, v177, v165
	ds_bpermute_b32 v170, v177, v169
	ds_bpermute_b32 v163, v177, v161
	s_waitcnt lgkmcnt(4)
	v_add_f32_e32 v160, v160, v166
	s_waitcnt lgkmcnt(3)
	v_add_f32_e32 v162, v162, v168
	s_waitcnt lgkmcnt(2)
	v_add_f32_e32 v164, v165, v167
	s_waitcnt lgkmcnt(1)
	v_add_f32_e32 v166, v169, v170
	s_waitcnt lgkmcnt(0)
	v_add_f32_e32 v168, v161, v163
	ds_bpermute_b32 v161, v178, v149
	ds_bpermute_b32 v163, v178, v158
	ds_bpermute_b32 v165, v178, v159
	ds_bpermute_b32 v167, v178, v160
	ds_bpermute_b32 v169, v178, v162
	ds_bpermute_b32 v170, v178, v164
	ds_bpermute_b32 v171, v178, v166
	ds_bpermute_b32 v172, v178, v168
	global_store_dwordx2 v[150:151], v[156:157], off offset:1024
	global_store_dwordx2 v[150:151], v[154:155], off offset:1536
	s_and_saveexec_b64 s[36:37], s[2:3]
	s_cbranch_execz .LBB0_37
	s_load_dwordx2 s[38:39], s[0:1], 0x50
	s_load_dwordx2 s[50:51], s[0:1], 0xd0
	v_lshlrev_b32_e32 v173, 2, v144
	s_waitcnt lgkmcnt(0)
	v_add_f32_e32 v149, v149, v161
	v_add_f32_e32 v157, v158, v163
	global_load_dword v150, v173, s[38:39] nt
	v_cndmask_b32_e64 v149, 0, v149, s[18:19]
	v_add_f32_e32 v156, v159, v165
	v_cndmask_b32_e64 v149, v149, v157, s[16:17]
	v_add_f32_e32 v155, v160, v167
	v_cndmask_b32_e64 v149, v149, v156, s[14:15]
	v_add_f32_e32 v154, v162, v169
	v_cndmask_b32_e64 v149, v149, v155, s[12:13]
	v_add_f32_e32 v153, v164, v170
	v_cndmask_b32_e64 v149, v149, v154, s[10:11]
	v_add_f32_e32 v152, v166, v171
	v_cndmask_b32_e64 v149, v149, v153, s[8:9]
	v_add_f32_e32 v151, v168, v172
	v_cndmask_b32_e64 v149, v149, v152, s[6:7]
	v_cndmask_b32_e64 v149, v149, v151, s[4:5]
	s_add_i32 s26, s20, 0xffffc000
	s_and_b64 s[30:31], s[30:31], exec
	s_cselect_b32 s31, s35, 0
	s_cselect_b32 s30, s34, s26
	s_cselect_b32 s26, s48, 0xd680000
	s_lshl_b64 s[30:31], s[30:31], 5
	s_add_u32 s30, s50, s30
	s_addc_u32 s31, s51, s31
	s_add_u32 s30, s30, s26
	s_addc_u32 s31, s31, 0
	s_waitcnt vmcnt(0)
	v_add_f32_e32 v149, v149, v150
	v_mul_f32_e64 v150, |v149|, s40
	v_fma_f32 v151, |v149|, s40, -v150
	v_rndne_f32_e32 v152, v150
	v_fma_f32 v151, |v149|, s41, v151
	v_sub_f32_e32 v150, v150, v152
	v_add_f32_e32 v150, v150, v151
	v_cvt_i32_f32_e32 v152, v152
	v_exp_f32_e32 v150, v150
	v_cmp_ngt_f32_e64 vcc, |v149|, s42
	v_min_f32_e32 v164, 0, v149
	v_ldexp_f32 v150, v150, v152
	v_cndmask_b32_e32 v150, 0, v150, vcc
	v_cmp_nlt_f32_e64 vcc, |v149|, s43
	s_nop 1
	v_cndmask_b32_e32 v165, v181, v150, vcc
	v_add_f32_e32 v149, 1.0, v165
	v_add_f32_e32 v152, -1.0, v149
	v_frexp_mant_f32_e32 v153, v149
	v_cvt_f64_f32_e32 v[150:151], v149
	v_sub_f32_e32 v154, v152, v149
	v_frexp_exp_i32_f64_e32 v150, v[150:151]
	v_cmp_gt_f32_e32 vcc, s45, v153
	v_sub_f32_e32 v152, v165, v152
	v_add_f32_e32 v151, 1.0, v154
	v_subbrev_co_u32_e32 v150, vcc, 0, v150, vcc
	v_add_f32_e32 v151, v152, v151
	v_sub_u32_e32 v152, 0, v150
	v_ldexp_f32 v149, v149, v152
	v_ldexp_f32 v151, v151, v152
	v_add_f32_e32 v152, -1.0, v149
	v_add_f32_e32 v154, 1.0, v149
	v_add_f32_e32 v153, 1.0, v152
	v_add_f32_e32 v155, -1.0, v154
	v_sub_f32_e32 v153, v149, v153
	v_sub_f32_e32 v149, v149, v155
	v_add_f32_e32 v149, v151, v149
	v_add_f32_e32 v155, v151, v153
	v_add_f32_e32 v151, v154, v149
	v_rcp_f32_e32 v158, v151
	v_add_f32_e32 v153, v152, v155
	v_sub_f32_e32 v154, v154, v151
	v_add_f32_e32 v149, v149, v154
	v_mul_f32_e32 v160, v153, v158
	v_mul_f32_e32 v154, v151, v160
	v_fma_f32 v156, v160, v151, -v154
	v_sub_f32_e32 v152, v152, v153
	v_fmac_f32_e32 v156, v160, v149
	v_add_f32_e32 v159, v155, v152
	v_add_f32_e32 v152, v154, v156
	v_sub_f32_e32 v155, v153, v152
	v_mov_b32_e32 v157, v152
	v_pk_add_f32 v[152:153], v[152:153], v[154:155] neg_lo:[0,1] neg_hi:[0,1]
	v_cvt_f32_i32_e32 v150, v150
	v_pk_add_f32 v[152:153], v[152:153], v[156:157] neg_lo:[0,1] neg_hi:[0,1]
	v_cmp_neq_f32_e32 vcc, s44, v165
	v_add_f32_e32 v153, v159, v153
	v_add_f32_e32 v152, v152, v153
	v_add_f32_e32 v153, v155, v152
	v_mul_f32_e32 v157, v158, v153
	v_mul_f32_e32 v154, v151, v157
	v_fma_f32 v156, v157, v151, -v154
	v_sub_f32_e32 v155, v155, v153
	v_fmac_f32_e32 v156, v157, v149
	v_add_f32_e32 v159, v152, v155
	v_add_f32_e32 v161, v160, v157
	v_add_f32_e32 v152, v154, v156
	v_sub_f32_e32 v151, v161, v160
	v_sub_f32_e32 v155, v153, v152
	v_sub_f32_e32 v149, v157, v151
	v_mov_b32_e32 v157, v152
	v_pk_add_f32 v[152:153], v[152:153], v[154:155] neg_lo:[0,1] neg_hi:[0,1]
	s_nop 0
	v_pk_add_f32 v[152:153], v[152:153], v[156:157] neg_lo:[0,1] neg_hi:[0,1]
	s_nop 0
	v_add_f32_e32 v151, v159, v153
	v_add_f32_e32 v151, v152, v151
	v_add_f32_e32 v151, v155, v151
	v_mul_f32_e32 v151, v158, v151
	v_add_f32_e32 v149, v149, v151
	v_add_f32_e32 v151, v161, v149
	v_mul_f32_e32 v152, v151, v151
	v_sub_f32_e32 v154, v151, v161
	v_fmamk_f32 v155, v152, 0x3e9b6dac, v180
	v_ldexp_f32 v153, v151, 1
	v_sub_f32_e32 v154, v149, v154
	v_mul_f32_e32 v151, v151, v152
	v_fmaak_f32 v149, v152, v155, 0x3f2aaada
	v_ldexp_f32 v157, v154, 1
	v_pk_mul_f32 v[154:155], v[150:151], v[148:149]
	s_nop 0
	v_fma_f32 v152, v150, s46, -v154
	v_fmac_f32_e32 v152, 0xb102e308, v150
	v_pk_add_f32 v[150:151], v[154:155], v[152:153]
	v_mov_b32_e32 v156, v154
	v_sub_f32_e32 v149, v151, v153
	v_sub_f32_e32 v149, v155, v149
	v_add_f32_e32 v157, v157, v149
	v_pk_add_f32 v[158:159], v[150:151], v[154:155] neg_lo:[0,1] neg_hi:[0,1]
	v_pk_add_f32 v[154:155], v[150:151], v[156:157]
	v_mov_b32_e32 v153, v150
	v_mov_b32_e32 v159, v155
	v_pk_add_f32 v[162:163], v[152:153], v[158:159] neg_lo:[0,1] neg_hi:[0,1]
	v_pk_add_f32 v[152:153], v[152:153], v[158:159]
	v_mov_b32_e32 v161, v150
	v_pk_add_f32 v[158:159], v[152:153], v[150:151] op_sel:[1,0] op_sel_hi:[0,1] neg_lo:[0,1] neg_hi:[0,1]
	v_mov_b32_e32 v160, v157
	v_mov_b32_e32 v156, v155
	v_mov_b32_e32 v157, v153
	v_pk_mov_b32 v[150:151], v[150:151], v[158:159] op_sel:[1,0]
	v_pk_add_f32 v[154:155], v[154:155], v[158:159] op_sel_hi:[1,0] neg_lo:[0,1] neg_hi:[0,1]
	v_pk_add_f32 v[150:151], v[156:157], v[150:151] neg_lo:[0,1] neg_hi:[0,1]
	v_mov_b32_e32 v154, v162
	v_pk_add_f32 v[150:151], v[160:161], v[150:151] neg_lo:[0,1] neg_hi:[0,1]
	v_mov_b32_e32 v163, v153
	v_pk_add_f32 v[154:155], v[154:155], v[150:151]
	s_nop 0
	v_pk_add_f32 v[156:157], v[154:155], v[154:155] op_sel:[0,1] op_sel_hi:[1,0]
	s_nop 0
	v_pk_add_f32 v[152:153], v[152:153], v[156:157] op_sel:[1,0] op_sel_hi:[0,1]
	v_mov_b32_e32 v155, v152
	v_mov_b32_e32 v151, v156
	v_pk_add_f32 v[156:157], v[154:155], v[162:163] neg_lo:[0,1] neg_hi:[0,1]
	s_nop 0
	v_sub_f32_e32 v149, v154, v156
	v_pk_add_f32 v[150:151], v[150:151], v[156:157] neg_lo:[0,1] neg_hi:[0,1]
	v_sub_f32_e32 v149, v162, v149
	v_add_f32_e32 v149, v150, v149
	v_add_f32_e32 v149, v149, v151
	v_add_f32_e32 v149, v152, v149
	v_cndmask_b32_e32 v149, v181, v149, vcc
	v_cmp_lt_f32_e64 vcc, |v165|, s47
	s_nop 1
	v_cndmask_b32_e32 v149, v149, v165, vcc
	v_sub_f32_e32 v149, v164, v149
	global_store_dword v173, v149, s[30:31]
	s_branch .LBB0_37
